# prologue weight transposes: the 16 serial LDS read round trips of each item issued together (15+1) before the bf16 conversions
# baseline (speedup 1.0000x reference)
.LBB0_798:
	s_mul_hi_i32 s0, s13, 0x82082083
	s_add_i32 s0, s0, s13
	s_lshr_b32 s1, s0, 31
	s_ashr_i32 s0, s0, 12
	s_add_i32 s0, s0, s1
	s_mul_i32 s1, s0, 0xffffe080
	s_add_i32 s15, s13, s1
	s_cmp_gt_i32 s15, -1
	s_mov_b64 s[2:3], -1
	s_cbranch_scc0 .LBB0_820
	s_cmpk_gt_u32 s15, 0xb7f
	s_cbranch_scc0 .LBB0_817
	s_cmpk_gt_u32 s15, 0xc7f
	s_cbranch_scc0 .LBB0_814
	s_cmpk_gt_u32 s15, 0xcff
	s_cbranch_scc0 .LBB0_811
	s_cmpk_gt_u32 s15, 0xeff
	s_cbranch_scc0 .LBB0_808
	s_cmpk_gt_u32 s15, 0x19ff
	s_mul_hi_i32 s1, s0, 0xb00000
	s_mul_i32 s16, s0, 0xb00000
	s_cbranch_scc0 .LBB0_805
	v_readlane_b32 s2, v252, 3
	s_mul_i32 s17, s0, 0x580000
	v_lshlrev_b32_e32 v8, 2, v0
	v_mov_b32_e32 v6, s2
	ds_read_b64 v[6:7], v6
	v_mov_b32_e32 v9, v2
	s_waitcnt lgkmcnt(0)
	v_readfirstlane_b32 s2, v6
	v_readfirstlane_b32 s3, v7
	s_add_u32 s22, s2, s16
	s_addc_u32 s3, s3, s1
	s_mul_hi_i32 s2, s0, 0x580000
	s_add_u32 s18, s70, s17
	s_addc_u32 s19, s74, s2
	s_mul_i32 s2, s0, 0xffffc100
	s_add_i32 s2, s12, s2
	s_andn2_b32 s2, s2, 63
	s_and_b32 s17, s14, 0x3e0
	s_addk_i32 s2, 0xcc00
	s_lshl_b32 s23, s17, 2
	v_or_b32_e32 v6, s2, v1
	s_add_u32 s22, s22, s23
	s_addc_u32 s23, s3, 0
	v_ashrrev_i32_e32 v7, 31, v6
	v_lshl_add_u64 v[8:9], s[22:23], 0, v[8:9]
	v_lshlrev_b64 v[16:17], 12, v[6:7]
	v_lshl_add_u64 v[16:17], v[8:9], 0, v[16:17]
	flat_load_dword v15, v[16:17] nt
	v_or_b32_e32 v16, 2, v6
	v_ashrrev_i32_e32 v17, 31, v16
	v_lshlrev_b64 v[16:17], 12, v[16:17]
	v_lshl_add_u64 v[16:17], v[8:9], 0, v[16:17]
	flat_load_dword v18, v[16:17] nt
	v_or_b32_e32 v16, 4, v6
	v_ashrrev_i32_e32 v17, 31, v16
	v_lshlrev_b64 v[16:17], 12, v[16:17]
	v_lshl_add_u64 v[16:17], v[8:9], 0, v[16:17]
	flat_load_dword v19, v[16:17] nt
	v_or_b32_e32 v16, 6, v6
	v_ashrrev_i32_e32 v17, 31, v16
	v_lshlrev_b64 v[16:17], 12, v[16:17]
	v_lshl_add_u64 v[16:17], v[8:9], 0, v[16:17]
	flat_load_dword v20, v[16:17] nt
	v_or_b32_e32 v16, 8, v6
	v_ashrrev_i32_e32 v17, 31, v16
	v_lshlrev_b64 v[16:17], 12, v[16:17]
	v_lshl_add_u64 v[16:17], v[8:9], 0, v[16:17]
	flat_load_dword v21, v[16:17] nt
	v_or_b32_e32 v16, 10, v6
	v_ashrrev_i32_e32 v17, 31, v16
	v_lshlrev_b64 v[16:17], 12, v[16:17]
	v_lshl_add_u64 v[16:17], v[8:9], 0, v[16:17]
	flat_load_dword v22, v[16:17] nt
	v_or_b32_e32 v16, 12, v6
	v_ashrrev_i32_e32 v17, 31, v16
	v_lshlrev_b64 v[16:17], 12, v[16:17]
	v_lshl_add_u64 v[16:17], v[8:9], 0, v[16:17]
	flat_load_dword v23, v[16:17] nt
	v_or_b32_e32 v16, 14, v6
	v_ashrrev_i32_e32 v17, 31, v16
	v_lshlrev_b64 v[16:17], 12, v[16:17]
	v_lshl_add_u64 v[16:17], v[8:9], 0, v[16:17]
	flat_load_dword v24, v[16:17] nt
	v_or_b32_e32 v16, 16, v6
	v_ashrrev_i32_e32 v17, 31, v16
	v_lshlrev_b64 v[16:17], 12, v[16:17]
	v_lshl_add_u64 v[16:17], v[8:9], 0, v[16:17]
	flat_load_dword v25, v[16:17] nt
	v_or_b32_e32 v16, 18, v6
	v_ashrrev_i32_e32 v17, 31, v16
	v_lshlrev_b64 v[16:17], 12, v[16:17]
	v_lshl_add_u64 v[16:17], v[8:9], 0, v[16:17]
	flat_load_dword v26, v[16:17] nt
	v_or_b32_e32 v16, 20, v6
	v_ashrrev_i32_e32 v17, 31, v16
	v_lshlrev_b64 v[16:17], 12, v[16:17]
	v_lshl_add_u64 v[16:17], v[8:9], 0, v[16:17]
	flat_load_dword v27, v[16:17] nt
	v_or_b32_e32 v16, 22, v6
	v_ashrrev_i32_e32 v17, 31, v16
	v_lshlrev_b64 v[16:17], 12, v[16:17]
	v_lshl_add_u64 v[16:17], v[8:9], 0, v[16:17]
	flat_load_dword v28, v[16:17] nt
	v_or_b32_e32 v16, 24, v6
	v_ashrrev_i32_e32 v17, 31, v16
	v_lshlrev_b64 v[16:17], 12, v[16:17]
	v_lshl_add_u64 v[16:17], v[8:9], 0, v[16:17]
	flat_load_dword v29, v[16:17] nt
	v_or_b32_e32 v16, 26, v6
	v_ashrrev_i32_e32 v17, 31, v16
	v_lshlrev_b64 v[16:17], 12, v[16:17]
	v_lshl_add_u64 v[16:17], v[8:9], 0, v[16:17]
	flat_load_dword v30, v[16:17] nt
	v_or_b32_e32 v16, 28, v6
	v_ashrrev_i32_e32 v17, 31, v16
	v_lshlrev_b64 v[16:17], 12, v[16:17]
	v_lshl_add_u64 v[16:17], v[8:9], 0, v[16:17]
	flat_load_dword v31, v[16:17] nt
	v_or_b32_e32 v16, 30, v6
	v_ashrrev_i32_e32 v17, 31, v16
	v_lshlrev_b64 v[16:17], 12, v[16:17]
	v_lshl_add_u64 v[16:17], v[8:9], 0, v[16:17]
	flat_load_dword v32, v[16:17] nt
	v_or_b32_e32 v16, 32, v6
	v_ashrrev_i32_e32 v17, 31, v16
	v_lshlrev_b64 v[16:17], 12, v[16:17]
	v_lshl_add_u64 v[16:17], v[8:9], 0, v[16:17]
	flat_load_dword v33, v[16:17] nt
	v_or_b32_e32 v16, 34, v6
	v_ashrrev_i32_e32 v17, 31, v16
	v_lshlrev_b64 v[16:17], 12, v[16:17]
	v_lshl_add_u64 v[16:17], v[8:9], 0, v[16:17]
	flat_load_dword v34, v[16:17] nt
	v_or_b32_e32 v16, 36, v6
	v_ashrrev_i32_e32 v17, 31, v16
	v_lshlrev_b64 v[16:17], 12, v[16:17]
	v_lshl_add_u64 v[16:17], v[8:9], 0, v[16:17]
	flat_load_dword v35, v[16:17] nt
	v_or_b32_e32 v16, 38, v6
	v_ashrrev_i32_e32 v17, 31, v16
	v_lshlrev_b64 v[16:17], 12, v[16:17]
	v_lshl_add_u64 v[16:17], v[8:9], 0, v[16:17]
	flat_load_dword v36, v[16:17] nt
	v_or_b32_e32 v16, 40, v6
	v_ashrrev_i32_e32 v17, 31, v16
	v_lshlrev_b64 v[16:17], 12, v[16:17]
	v_lshl_add_u64 v[16:17], v[8:9], 0, v[16:17]
	flat_load_dword v37, v[16:17] nt
	v_or_b32_e32 v16, 42, v6
	v_ashrrev_i32_e32 v17, 31, v16
	v_lshlrev_b64 v[16:17], 12, v[16:17]
	v_lshl_add_u64 v[16:17], v[8:9], 0, v[16:17]
	flat_load_dword v38, v[16:17] nt
	v_or_b32_e32 v16, 44, v6
	v_ashrrev_i32_e32 v17, 31, v16
	v_lshlrev_b64 v[16:17], 12, v[16:17]
	v_lshl_add_u64 v[16:17], v[8:9], 0, v[16:17]
	flat_load_dword v39, v[16:17] nt
	v_or_b32_e32 v16, 46, v6
	v_ashrrev_i32_e32 v17, 31, v16
	v_lshlrev_b64 v[16:17], 12, v[16:17]
	v_lshl_add_u64 v[16:17], v[8:9], 0, v[16:17]
	flat_load_dword v40, v[16:17] nt
	v_or_b32_e32 v16, 48, v6
	v_ashrrev_i32_e32 v17, 31, v16
	v_lshlrev_b64 v[16:17], 12, v[16:17]
	v_lshl_add_u64 v[16:17], v[8:9], 0, v[16:17]
	flat_load_dword v41, v[16:17] nt
	v_or_b32_e32 v16, 50, v6
	v_ashrrev_i32_e32 v17, 31, v16
	v_lshlrev_b64 v[16:17], 12, v[16:17]
	v_lshl_add_u64 v[16:17], v[8:9], 0, v[16:17]
	flat_load_dword v42, v[16:17] nt
	v_or_b32_e32 v16, 52, v6
	v_ashrrev_i32_e32 v17, 31, v16
	v_lshlrev_b64 v[16:17], 12, v[16:17]
	v_lshl_add_u64 v[16:17], v[8:9], 0, v[16:17]
	flat_load_dword v43, v[16:17] nt
	v_or_b32_e32 v16, 54, v6
	v_ashrrev_i32_e32 v17, 31, v16
	v_lshlrev_b64 v[16:17], 12, v[16:17]
	v_lshl_add_u64 v[16:17], v[8:9], 0, v[16:17]
	flat_load_dword v44, v[16:17] nt
	v_or_b32_e32 v16, 56, v6
	v_ashrrev_i32_e32 v17, 31, v16
	v_lshlrev_b64 v[16:17], 12, v[16:17]
	v_lshl_add_u64 v[16:17], v[8:9], 0, v[16:17]
	flat_load_dword v45, v[16:17] nt
	v_or_b32_e32 v16, 58, v6
	v_ashrrev_i32_e32 v17, 31, v16
	v_lshlrev_b64 v[16:17], 12, v[16:17]
	v_lshl_add_u64 v[16:17], v[8:9], 0, v[16:17]
	flat_load_dword v46, v[16:17] nt
	v_or_b32_e32 v16, 60, v6
	v_or_b32_e32 v6, 62, v6
	v_ashrrev_i32_e32 v17, 31, v16
	v_ashrrev_i32_e32 v7, 31, v6
	v_lshlrev_b64 v[16:17], 12, v[16:17]
	v_lshlrev_b64 v[6:7], 12, v[6:7]
	v_lshl_add_u64 v[16:17], v[8:9], 0, v[16:17]
	v_lshl_add_u64 v[6:7], v[8:9], 0, v[6:7]
	flat_load_dword v16, v[16:17] nt
	s_ashr_i32 s3, s2, 31
	flat_load_dword v6, v[6:7] nt
	v_add_u32_e32 v7, 0x400, v5
	s_waitcnt vmcnt(0) lgkmcnt(0)
	ds_write2_b32 v5, v15, v18 offset1:66
	ds_write2_b32 v5, v19, v20 offset0:132 offset1:198
	ds_write2_b32 v7, v21, v22 offset0:8 offset1:74
	ds_write2_b32 v7, v23, v24 offset0:140 offset1:206
	v_add_u32_e32 v7, 0x800, v5
	ds_write2_b32 v7, v25, v26 offset0:16 offset1:82
	ds_write2_b32 v7, v27, v28 offset0:148 offset1:214
	v_add_u32_e32 v7, 0xc00, v5
	ds_write2_b32 v7, v29, v30 offset0:24 offset1:90
	ds_write2_b32 v7, v31, v32 offset0:156 offset1:222
	v_add_u32_e32 v7, 0x1000, v5
	ds_write2_b32 v7, v33, v34 offset0:32 offset1:98
	ds_write2_b32 v7, v35, v36 offset0:164 offset1:230
	v_add_u32_e32 v7, 0x1400, v5
	ds_write2_b32 v7, v37, v38 offset0:40 offset1:106
	ds_write2_b32 v7, v39, v40 offset0:172 offset1:238
	v_add_u32_e32 v7, 0x1800, v5
	ds_write2_b32 v7, v41, v42 offset0:48 offset1:114
	ds_write2_b32 v7, v43, v44 offset0:180 offset1:246
	v_add_u32_e32 v7, 0x1c00, v5
	ds_write2_b32 v7, v45, v46 offset0:56 offset1:122
	ds_write2_b32 v7, v16, v6 offset0:188 offset1:254
	s_waitcnt lgkmcnt(0)
	ds_read2_b32 v[96:97], v11 offset1:33
	ds_read2_b32 v[98:99], v11 offset0:66 offset1:99
	ds_read2_b32 v[100:101], v11 offset0:132 offset1:165
	ds_read2_b32 v[102:103], v11 offset0:198 offset1:231
	ds_read2_b32 v[104:105], v11 offset0:8 offset1:41
	ds_read2_b32 v[106:107], v11 offset0:74 offset1:107
	ds_read2_b32 v[108:109], v11 offset0:140 offset1:173
	ds_read2_b32 v[110:111], v11 offset0:206 offset1:239
	ds_read2_b32 v[112:113], v11 offset0:16 offset1:49
	ds_read2_b32 v[114:115], v11 offset0:82 offset1:115
	ds_read2_b32 v[116:117], v11 offset0:148 offset1:181
	ds_read2_b32 v[118:119], v11 offset0:214 offset1:247
	ds_read2_b32 v[120:121], v11 offset0:24 offset1:57
	ds_read2_b32 v[122:123], v11 offset0:90 offset1:123
	ds_read2_b32 v[124:125], v11 offset0:156 offset1:189
	s_waitcnt lgkmcnt(7)
	ds_read2_b32 v[126:127], v11 offset0:222 offset1:255
	v_cvt_pk_bf16_f32 v16, v96, v97
	v_cvt_pk_bf16_f32 v17, v98, v99
	s_lshl_b64 s[2:3], s[2:3], 1
	v_cvt_pk_bf16_f32 v18, v100, v101
	s_add_u32 s2, s18, s2
	v_cvt_pk_bf16_f32 v19, v102, v103
	v_or_b32_e32 v8, s17, v10
	s_addc_u32 s3, s19, s3
	v_lshlrev_b32_e32 v6, 1, v4
	v_mov_b32_e32 v7, v2
	v_mul_u32_u24_e32 v8, 0xb00, v8
	v_lshl_add_u64 v[6:7], s[2:3], 0, v[6:7]
	v_lshlrev_b32_e32 v8, 1, v8
	v_mov_b32_e32 v9, v2
	v_lshl_add_u64 v[8:9], v[6:7], 0, v[8:9]
	global_store_dwordx4 v[8:9], v[16:19], off
	s_nop 1
	s_mov_b32 s23, 0xffff
	v_cvt_pk_bf16_f32 v16, v104, v105
	v_cvt_pk_bf16_f32 v17, v106, v107
	v_cvt_pk_bf16_f32 v18, v108, v109
	v_cvt_pk_bf16_f32 v19, v110, v111
	v_or_b32_e32 v8, s17, v12
	v_mul_u32_u24_e32 v8, 0xb00, v8
	v_lshlrev_b32_e32 v8, 1, v8
	v_mov_b32_e32 v9, v2
	v_lshl_add_u64 v[8:9], v[6:7], 0, v[8:9]
	global_store_dwordx4 v[8:9], v[16:19], off
	s_nop 1
	s_waitcnt lgkmcnt(0)
	s_mov_b32 s19, s69
	v_cvt_pk_bf16_f32 v16, v112, v113
	v_cvt_pk_bf16_f32 v17, v114, v115
	v_cvt_pk_bf16_f32 v18, v116, v117
	v_cvt_pk_bf16_f32 v19, v118, v119
	v_or_b32_e32 v8, s17, v13
	v_mul_u32_u24_e32 v8, 0xb00, v8
	v_lshlrev_b32_e32 v8, 1, v8
	v_mov_b32_e32 v9, v2
	v_lshl_add_u64 v[8:9], v[6:7], 0, v[8:9]
	global_store_dwordx4 v[8:9], v[16:19], off
	s_nop 1
	s_mov_b64 s[2:3], 0
	v_cvt_pk_bf16_f32 v16, v120, v121
	v_cvt_pk_bf16_f32 v17, v122, v123
	v_cvt_pk_bf16_f32 v18, v124, v125
	v_cvt_pk_bf16_f32 v19, v126, v127
	v_or_b32_e32 v8, s17, v14
	v_mul_u32_u24_e32 v8, 0xb00, v8
	v_lshlrev_b32_e32 v8, 1, v8
	v_mov_b32_e32 v9, v2
	v_lshl_add_u64 v[6:7], v[6:7], 0, v[8:9]
	global_store_dwordx4 v[6:7], v[16:19], off
	s_waitcnt lgkmcnt(0)
.LBB0_805:
	s_andn2_b64 vcc, exec, s[2:3]
	s_cbranch_vccnz .LBB0_807
	s_add_i32 s2, s15, 0xf100
	s_and_b32 s3, s2, 0xffff
	s_mul_i32 s3, s3, 0xba2f
	s_lshr_b32 s3, s3, 23
	s_mul_i32 s17, s3, 0xb0
	s_sub_i32 s2, s2, s17
	s_lshl_b32 s17, s2, 5
	s_and_b32 s17, s17, 0xffe0
	s_and_b32 s2, s2, 0xffff
	s_add_i32 s18, s17, 0xfffff500
	s_cmpk_lt_u32 s2, 0x58
	s_cselect_b32 s2, s17, s18
	s_cselect_b32 s18, 0, 0x80
	s_lshl_b32 s19, s2, 1
	s_and_b32 s2, s2, 0x60
	s_or_b32 s2, s2, s18
	v_readlane_b32 s18, v252, 4
	s_and_b32 s19, s19, 0xffffff00
	s_or_b32 s2, s2, s19
	v_mov_b32_e32 v6, s18
	ds_read_b64 v[6:7], v6
	s_mul_i32 s23, s0, 0x1600000
	s_mul_hi_i32 s22, s0, 0x1600000
	v_lshl_or_b32 v8, s3, 6, v1
	v_mul_u32_u24_e32 v8, 0x1600, v8
	s_waitcnt lgkmcnt(0)
	v_readfirstlane_b32 s18, v6
	v_readfirstlane_b32 s19, v7
	s_add_u32 s18, s18, s23
	s_addc_u32 s19, s19, s22
	s_add_u32 s16, s77, s16
	s_addc_u32 s1, s79, s1
	s_lshl_b32 s17, s17, 2
	s_add_u32 s18, s18, s17
	s_addc_u32 s19, s19, 0
	v_lshlrev_b32_e32 v6, 2, v0
	v_mov_b32_e32 v7, v2
	v_lshl_add_u64 v[6:7], s[18:19], 0, v[6:7]
	v_lshlrev_b32_e32 v8, 2, v8
	v_mov_b32_e32 v9, v2
	v_lshl_add_u64 v[6:7], v[6:7], 0, v[8:9]
	s_mov_b32 s17, 0xb000
	v_add_co_u32_e32 v8, vcc, s17, v6
	s_mov_b32 s17, 0x16000
	s_nop 0
	v_addc_co_u32_e32 v9, vcc, 0, v7, vcc
	flat_load_dword v15, v[6:7] nt
	flat_load_dword v16, v[8:9] nt
	v_add_co_u32_e32 v8, vcc, s17, v6
	s_mov_b32 s17, 0x21000
	s_nop 0
	v_addc_co_u32_e32 v9, vcc, 0, v7, vcc
	flat_load_dword v17, v[8:9] nt
	v_add_co_u32_e32 v8, vcc, s17, v6
	s_mov_b32 s17, 0x2c000
	s_nop 0
	v_addc_co_u32_e32 v9, vcc, 0, v7, vcc
	flat_load_dword v18, v[8:9] nt
	v_add_co_u32_e32 v8, vcc, s17, v6
	s_mov_b32 s17, 0x37000
	s_nop 0
	v_addc_co_u32_e32 v9, vcc, 0, v7, vcc
	flat_load_dword v19, v[8:9] nt
	v_add_co_u32_e32 v8, vcc, s17, v6
	s_mov_b32 s17, 0x42000
	s_nop 0
	v_addc_co_u32_e32 v9, vcc, 0, v7, vcc
	flat_load_dword v20, v[8:9] nt
	v_add_co_u32_e32 v8, vcc, s17, v6
	s_mov_b32 s17, 0x4d000
	s_nop 0
	v_addc_co_u32_e32 v9, vcc, 0, v7, vcc
	flat_load_dword v21, v[8:9] nt
	v_add_co_u32_e32 v8, vcc, s17, v6
	s_mov_b32 s17, 0x58000
	s_nop 0
	v_addc_co_u32_e32 v9, vcc, 0, v7, vcc
	flat_load_dword v22, v[8:9] nt
	v_add_co_u32_e32 v8, vcc, s17, v6
	s_mov_b32 s17, 0x63000
	s_nop 0
	v_addc_co_u32_e32 v9, vcc, 0, v7, vcc
	flat_load_dword v23, v[8:9] nt
	v_add_co_u32_e32 v8, vcc, s17, v6
	s_mov_b32 s17, 0x6e000
	s_nop 0
	v_addc_co_u32_e32 v9, vcc, 0, v7, vcc
	flat_load_dword v24, v[8:9] nt
	v_add_co_u32_e32 v8, vcc, s17, v6
	s_mov_b32 s17, 0x79000
	s_nop 0
	v_addc_co_u32_e32 v9, vcc, 0, v7, vcc
	flat_load_dword v25, v[8:9] nt
	v_add_co_u32_e32 v8, vcc, s17, v6
	s_mov_b32 s17, 0x84000
	s_nop 0
	v_addc_co_u32_e32 v9, vcc, 0, v7, vcc
	flat_load_dword v26, v[8:9] nt
	v_add_co_u32_e32 v8, vcc, s17, v6
	s_mov_b32 s17, 0x8f000
	s_nop 0
	v_addc_co_u32_e32 v9, vcc, 0, v7, vcc
	flat_load_dword v27, v[8:9] nt
	v_add_co_u32_e32 v8, vcc, s17, v6
	s_mov_b32 s17, 0x9a000
	s_nop 0
	v_addc_co_u32_e32 v9, vcc, 0, v7, vcc
	flat_load_dword v28, v[8:9] nt
	v_add_co_u32_e32 v8, vcc, s17, v6
	s_mov_b32 s17, 0xa5000
	s_nop 0
	v_addc_co_u32_e32 v9, vcc, 0, v7, vcc
	flat_load_dword v29, v[8:9] nt
	v_add_co_u32_e32 v8, vcc, s17, v6
	s_mov_b32 s17, 0xb0000
	s_nop 0
	v_addc_co_u32_e32 v9, vcc, 0, v7, vcc
	flat_load_dword v30, v[8:9] nt
	v_add_co_u32_e32 v8, vcc, s17, v6
	s_mov_b32 s17, 0xbb000
	s_nop 0
	v_addc_co_u32_e32 v9, vcc, 0, v7, vcc
	flat_load_dword v31, v[8:9] nt
	v_add_co_u32_e32 v8, vcc, s17, v6
	s_mov_b32 s17, 0xc6000
	s_nop 0
	v_addc_co_u32_e32 v9, vcc, 0, v7, vcc
	flat_load_dword v32, v[8:9] nt
	v_add_co_u32_e32 v8, vcc, s17, v6
	s_mov_b32 s17, 0xd1000
	s_nop 0
	v_addc_co_u32_e32 v9, vcc, 0, v7, vcc
	flat_load_dword v33, v[8:9] nt
	v_add_co_u32_e32 v8, vcc, s17, v6
	s_mov_b32 s17, 0xdc000
	s_nop 0
	v_addc_co_u32_e32 v9, vcc, 0, v7, vcc
	flat_load_dword v34, v[8:9] nt
	v_add_co_u32_e32 v8, vcc, s17, v6
	s_mov_b32 s17, 0xe7000
	s_nop 0
	v_addc_co_u32_e32 v9, vcc, 0, v7, vcc
	flat_load_dword v35, v[8:9] nt
	v_add_co_u32_e32 v8, vcc, s17, v6
	s_mov_b32 s17, 0xf2000
	s_nop 0
	v_addc_co_u32_e32 v9, vcc, 0, v7, vcc
	flat_load_dword v36, v[8:9] nt
	v_add_co_u32_e32 v8, vcc, s17, v6
	s_mov_b32 s17, 0xfd000
	s_nop 0
	v_addc_co_u32_e32 v9, vcc, 0, v7, vcc
	flat_load_dword v37, v[8:9] nt
	v_add_co_u32_e32 v8, vcc, s17, v6
	s_mov_b32 s17, 0x108000
	s_nop 0
	v_addc_co_u32_e32 v9, vcc, 0, v7, vcc
	flat_load_dword v38, v[8:9] nt
	v_add_co_u32_e32 v8, vcc, s17, v6
	s_mov_b32 s17, 0x113000
	s_nop 0
	v_addc_co_u32_e32 v9, vcc, 0, v7, vcc
	flat_load_dword v39, v[8:9] nt
	v_add_co_u32_e32 v8, vcc, s17, v6
	s_mov_b32 s17, 0x11e000
	s_nop 0
	v_addc_co_u32_e32 v9, vcc, 0, v7, vcc
	flat_load_dword v40, v[8:9] nt
	v_add_co_u32_e32 v8, vcc, s17, v6
	s_mov_b32 s17, 0x129000
	s_nop 0
	v_addc_co_u32_e32 v9, vcc, 0, v7, vcc
	flat_load_dword v41, v[8:9] nt
	v_add_co_u32_e32 v8, vcc, s17, v6
	s_mov_b32 s17, 0x134000
	s_nop 0
	v_addc_co_u32_e32 v9, vcc, 0, v7, vcc
	flat_load_dword v42, v[8:9] nt
	v_add_co_u32_e32 v8, vcc, s17, v6
	s_mov_b32 s17, 0x13f000
	s_nop 0
	v_addc_co_u32_e32 v9, vcc, 0, v7, vcc
	flat_load_dword v43, v[8:9] nt
	v_add_co_u32_e32 v8, vcc, s17, v6
	s_mov_b32 s17, 0x14a000
	s_nop 0
	v_addc_co_u32_e32 v9, vcc, 0, v7, vcc
	flat_load_dword v44, v[8:9] nt
	v_add_co_u32_e32 v8, vcc, s17, v6
	s_mov_b32 s17, 0x155000
	s_nop 0
	v_addc_co_u32_e32 v9, vcc, 0, v7, vcc
	v_add_co_u32_e32 v6, vcc, s17, v6
	flat_load_dword v8, v[8:9] nt
	s_nop 0
	v_addc_co_u32_e32 v7, vcc, 0, v7, vcc
	flat_load_dword v6, v[6:7] nt
	v_add_u32_e32 v7, 0x400, v5
	s_waitcnt vmcnt(0) lgkmcnt(0)
	ds_write2_b32 v5, v15, v16 offset1:66
	ds_write2_b32 v5, v17, v18 offset0:132 offset1:198
	ds_write2_b32 v7, v19, v20 offset0:8 offset1:74
	ds_write2_b32 v7, v21, v22 offset0:140 offset1:206
	v_add_u32_e32 v7, 0x800, v5
	ds_write2_b32 v7, v23, v24 offset0:16 offset1:82
	ds_write2_b32 v7, v25, v26 offset0:148 offset1:214
	v_add_u32_e32 v7, 0xc00, v5
	ds_write2_b32 v7, v27, v28 offset0:24 offset1:90
	ds_write2_b32 v7, v29, v30 offset0:156 offset1:222
	v_add_u32_e32 v7, 0x1000, v5
	ds_write2_b32 v7, v31, v32 offset0:32 offset1:98
	ds_write2_b32 v7, v33, v34 offset0:164 offset1:230
	v_add_u32_e32 v7, 0x1400, v5
	ds_write2_b32 v7, v35, v36 offset0:40 offset1:106
	ds_write2_b32 v7, v37, v38 offset0:172 offset1:238
	v_add_u32_e32 v7, 0x1800, v5
	ds_write2_b32 v7, v39, v40 offset0:48 offset1:114
	ds_write2_b32 v7, v41, v42 offset0:180 offset1:246
	v_add_u32_e32 v7, 0x1c00, v5
	ds_write2_b32 v7, v43, v44 offset0:56 offset1:122
	ds_write2_b32 v7, v8, v6 offset0:188 offset1:254
	s_waitcnt lgkmcnt(0)
	ds_read2_b32 v[96:97], v11 offset1:33
	ds_read2_b32 v[98:99], v11 offset0:66 offset1:99
	ds_read2_b32 v[100:101], v11 offset0:132 offset1:165
	ds_read2_b32 v[102:103], v11 offset0:198 offset1:231
	ds_read2_b32 v[104:105], v11 offset0:8 offset1:41
	ds_read2_b32 v[106:107], v11 offset0:74 offset1:107
	ds_read2_b32 v[108:109], v11 offset0:140 offset1:173
	ds_read2_b32 v[110:111], v11 offset0:206 offset1:239
	ds_read2_b32 v[112:113], v11 offset0:16 offset1:49
	ds_read2_b32 v[114:115], v11 offset0:82 offset1:115
	ds_read2_b32 v[116:117], v11 offset0:148 offset1:181
	ds_read2_b32 v[118:119], v11 offset0:214 offset1:247
	ds_read2_b32 v[120:121], v11 offset0:24 offset1:57
	ds_read2_b32 v[122:123], v11 offset0:90 offset1:123
	ds_read2_b32 v[124:125], v11 offset0:156 offset1:189
	s_waitcnt lgkmcnt(7)
	ds_read2_b32 v[126:127], v11 offset0:222 offset1:255
	v_cvt_pk_bf16_f32 v16, v96, v97
	v_cvt_pk_bf16_f32 v17, v98, v99
	s_lshl_b32 s3, s3, 7
	v_cvt_pk_bf16_f32 v18, v100, v101
	s_add_u32 s16, s16, s3
	v_cvt_pk_bf16_f32 v19, v102, v103
	v_or_b32_e32 v8, s2, v10
	s_addc_u32 s17, s1, 0
	v_lshlrev_b32_e32 v6, 1, v4
	v_mov_b32_e32 v7, v2
	v_ashrrev_i32_e32 v9, 31, v8
	v_lshl_add_u64 v[6:7], s[16:17], 0, v[6:7]
	v_lshlrev_b64 v[8:9], 11, v[8:9]
	v_lshl_add_u64 v[8:9], v[6:7], 0, v[8:9]
	global_store_dwordx4 v[8:9], v[16:19], off
	s_nop 1
	s_mov_b32 s23, 0xffff
	v_cvt_pk_bf16_f32 v16, v104, v105
	v_cvt_pk_bf16_f32 v17, v106, v107
	v_cvt_pk_bf16_f32 v18, v108, v109
	v_cvt_pk_bf16_f32 v19, v110, v111
	v_or_b32_e32 v8, s2, v12
	v_ashrrev_i32_e32 v9, 31, v8
	v_lshlrev_b64 v[8:9], 11, v[8:9]
	v_lshl_add_u64 v[8:9], v[6:7], 0, v[8:9]
	global_store_dwordx4 v[8:9], v[16:19], off
	s_nop 1
	s_waitcnt lgkmcnt(0)
	s_mov_b32 s19, s69
	v_cvt_pk_bf16_f32 v16, v112, v113
	v_cvt_pk_bf16_f32 v17, v114, v115
	v_cvt_pk_bf16_f32 v18, v116, v117
	v_cvt_pk_bf16_f32 v19, v118, v119
	v_or_b32_e32 v8, s2, v13
	v_ashrrev_i32_e32 v9, 31, v8
	v_lshlrev_b64 v[8:9], 11, v[8:9]
	v_lshl_add_u64 v[8:9], v[6:7], 0, v[8:9]
	global_store_dwordx4 v[8:9], v[16:19], off
	s_nop 1
	v_cvt_pk_bf16_f32 v16, v120, v121
	v_cvt_pk_bf16_f32 v17, v122, v123
	v_cvt_pk_bf16_f32 v18, v124, v125
	v_cvt_pk_bf16_f32 v19, v126, v127
	v_or_b32_e32 v8, s2, v14
	v_ashrrev_i32_e32 v9, 31, v8
	v_lshlrev_b64 v[8:9], 11, v[8:9]
	v_lshl_add_u64 v[6:7], v[6:7], 0, v[8:9]
	global_store_dwordx4 v[6:7], v[16:19], off
	s_waitcnt lgkmcnt(0)

.LBB0_808:
	s_andn2_b64 vcc, exec, s[2:3]
	s_cbranch_vccnz .LBB0_810
	v_readlane_b32 s1, v252, 5
	v_lshlrev_b32_e32 v8, 2, v0
	v_mov_b32_e32 v9, v2
	v_mov_b32_e32 v6, s1
	ds_read_b64 v[6:7], v6
	s_ashr_i32 s1, s0, 31
	s_lshl_b64 s[2:3], s[0:1], 22
	s_waitcnt lgkmcnt(0)
	v_readfirstlane_b32 s16, v6
	v_readfirstlane_b32 s17, v7
	s_add_u32 s16, s16, s2
	s_addc_u32 s17, s17, s3
	s_lshl_b64 s[2:3], s[0:1], 21
	s_add_u32 s2, s90, s2
	s_mul_i32 s1, s0, 0xffffc100
	s_addc_u32 s3, s91, s3
	s_add_i32 s1, s12, s1
	s_and_b32 s1, s1, 0x1fc0
	s_add_i32 s88, s1, 0xffffe600
	s_and_b32 s1, s14, 0x3e0
	s_lshl_b32 s18, s1, 2
	s_add_u32 s16, s16, s18
	v_or_b32_e32 v6, s88, v1
	s_addc_u32 s17, s17, 0
	v_mov_b32_e32 v7, v2
	v_lshl_add_u64 v[8:9], s[16:17], 0, v[8:9]
	v_lshlrev_b64 v[16:17], 12, v[6:7]
	v_lshl_add_u64 v[16:17], v[8:9], 0, v[16:17]
	flat_load_dword v15, v[16:17] nt
	v_or_b32_e32 v16, 2, v6
	v_mov_b32_e32 v17, v2
	v_lshlrev_b64 v[16:17], 12, v[16:17]
	v_lshl_add_u64 v[16:17], v[8:9], 0, v[16:17]
	flat_load_dword v18, v[16:17] nt
	v_or_b32_e32 v16, 4, v6
	v_mov_b32_e32 v17, v2
	v_lshlrev_b64 v[16:17], 12, v[16:17]
	v_lshl_add_u64 v[16:17], v[8:9], 0, v[16:17]
	flat_load_dword v19, v[16:17] nt
	v_or_b32_e32 v16, 6, v6
	v_mov_b32_e32 v17, v2
	v_lshlrev_b64 v[16:17], 12, v[16:17]
	v_lshl_add_u64 v[16:17], v[8:9], 0, v[16:17]
	flat_load_dword v20, v[16:17] nt
	v_or_b32_e32 v16, 8, v6
	v_mov_b32_e32 v17, v2
	v_lshlrev_b64 v[16:17], 12, v[16:17]
	v_lshl_add_u64 v[16:17], v[8:9], 0, v[16:17]
	flat_load_dword v21, v[16:17] nt
	v_or_b32_e32 v16, 10, v6
	v_mov_b32_e32 v17, v2
	v_lshlrev_b64 v[16:17], 12, v[16:17]
	v_lshl_add_u64 v[16:17], v[8:9], 0, v[16:17]
	flat_load_dword v22, v[16:17] nt
	v_or_b32_e32 v16, 12, v6
	v_mov_b32_e32 v17, v2
	v_lshlrev_b64 v[16:17], 12, v[16:17]
	v_lshl_add_u64 v[16:17], v[8:9], 0, v[16:17]
	flat_load_dword v23, v[16:17] nt
	v_or_b32_e32 v16, 14, v6
	v_mov_b32_e32 v17, v2
	v_lshlrev_b64 v[16:17], 12, v[16:17]
	v_lshl_add_u64 v[16:17], v[8:9], 0, v[16:17]
	flat_load_dword v24, v[16:17] nt
	v_or_b32_e32 v16, 16, v6
	v_mov_b32_e32 v17, v2
	v_lshlrev_b64 v[16:17], 12, v[16:17]
	v_lshl_add_u64 v[16:17], v[8:9], 0, v[16:17]
	flat_load_dword v25, v[16:17] nt
	v_or_b32_e32 v16, 18, v6
	v_mov_b32_e32 v17, v2
	v_lshlrev_b64 v[16:17], 12, v[16:17]
	v_lshl_add_u64 v[16:17], v[8:9], 0, v[16:17]
	flat_load_dword v26, v[16:17] nt
	v_or_b32_e32 v16, 20, v6
	v_mov_b32_e32 v17, v2
	v_lshlrev_b64 v[16:17], 12, v[16:17]
	v_lshl_add_u64 v[16:17], v[8:9], 0, v[16:17]
	flat_load_dword v27, v[16:17] nt
	v_or_b32_e32 v16, 22, v6
	v_mov_b32_e32 v17, v2
	v_lshlrev_b64 v[16:17], 12, v[16:17]
	v_lshl_add_u64 v[16:17], v[8:9], 0, v[16:17]
	flat_load_dword v28, v[16:17] nt
	v_or_b32_e32 v16, 24, v6
	v_mov_b32_e32 v17, v2
	v_lshlrev_b64 v[16:17], 12, v[16:17]
	v_lshl_add_u64 v[16:17], v[8:9], 0, v[16:17]
	flat_load_dword v29, v[16:17] nt
	v_or_b32_e32 v16, 26, v6
	v_mov_b32_e32 v17, v2
	v_lshlrev_b64 v[16:17], 12, v[16:17]
	v_lshl_add_u64 v[16:17], v[8:9], 0, v[16:17]
	flat_load_dword v30, v[16:17] nt
	v_or_b32_e32 v16, 28, v6
	v_mov_b32_e32 v17, v2
	v_lshlrev_b64 v[16:17], 12, v[16:17]
	v_lshl_add_u64 v[16:17], v[8:9], 0, v[16:17]
	flat_load_dword v31, v[16:17] nt
	v_or_b32_e32 v16, 30, v6
	v_mov_b32_e32 v17, v2
	v_lshlrev_b64 v[16:17], 12, v[16:17]
	v_lshl_add_u64 v[16:17], v[8:9], 0, v[16:17]
	flat_load_dword v32, v[16:17] nt
	v_or_b32_e32 v16, 32, v6
	v_mov_b32_e32 v17, v2
	v_lshlrev_b64 v[16:17], 12, v[16:17]
	v_lshl_add_u64 v[16:17], v[8:9], 0, v[16:17]
	flat_load_dword v33, v[16:17] nt
	v_or_b32_e32 v16, 34, v6
	v_mov_b32_e32 v17, v2
	v_lshlrev_b64 v[16:17], 12, v[16:17]
	v_lshl_add_u64 v[16:17], v[8:9], 0, v[16:17]
	flat_load_dword v34, v[16:17] nt
	v_or_b32_e32 v16, 36, v6
	v_mov_b32_e32 v17, v2
	v_lshlrev_b64 v[16:17], 12, v[16:17]
	v_lshl_add_u64 v[16:17], v[8:9], 0, v[16:17]
	flat_load_dword v35, v[16:17] nt
	v_or_b32_e32 v16, 38, v6
	v_mov_b32_e32 v17, v2
	v_lshlrev_b64 v[16:17], 12, v[16:17]
	v_lshl_add_u64 v[16:17], v[8:9], 0, v[16:17]
	flat_load_dword v36, v[16:17] nt
	v_or_b32_e32 v16, 40, v6
	v_mov_b32_e32 v17, v2
	v_lshlrev_b64 v[16:17], 12, v[16:17]
	v_lshl_add_u64 v[16:17], v[8:9], 0, v[16:17]
	flat_load_dword v37, v[16:17] nt
	v_or_b32_e32 v16, 42, v6
	v_mov_b32_e32 v17, v2
	v_lshlrev_b64 v[16:17], 12, v[16:17]
	v_lshl_add_u64 v[16:17], v[8:9], 0, v[16:17]
	flat_load_dword v38, v[16:17] nt
	v_or_b32_e32 v16, 44, v6
	v_mov_b32_e32 v17, v2
	v_lshlrev_b64 v[16:17], 12, v[16:17]
	v_lshl_add_u64 v[16:17], v[8:9], 0, v[16:17]
	flat_load_dword v39, v[16:17] nt
	v_or_b32_e32 v16, 46, v6
	v_mov_b32_e32 v17, v2
	v_lshlrev_b64 v[16:17], 12, v[16:17]
	v_lshl_add_u64 v[16:17], v[8:9], 0, v[16:17]
	flat_load_dword v40, v[16:17] nt
	v_or_b32_e32 v16, 48, v6
	v_mov_b32_e32 v17, v2
	v_lshlrev_b64 v[16:17], 12, v[16:17]
	v_lshl_add_u64 v[16:17], v[8:9], 0, v[16:17]
	flat_load_dword v41, v[16:17] nt
	v_or_b32_e32 v16, 50, v6
	v_mov_b32_e32 v17, v2
	v_lshlrev_b64 v[16:17], 12, v[16:17]
	v_lshl_add_u64 v[16:17], v[8:9], 0, v[16:17]
	flat_load_dword v42, v[16:17] nt
	v_or_b32_e32 v16, 52, v6
	v_mov_b32_e32 v17, v2
	v_lshlrev_b64 v[16:17], 12, v[16:17]
	v_lshl_add_u64 v[16:17], v[8:9], 0, v[16:17]
	flat_load_dword v43, v[16:17] nt
	v_or_b32_e32 v16, 54, v6
	v_mov_b32_e32 v17, v2
	v_lshlrev_b64 v[16:17], 12, v[16:17]
	v_lshl_add_u64 v[16:17], v[8:9], 0, v[16:17]
	flat_load_dword v44, v[16:17] nt
	v_or_b32_e32 v16, 56, v6
	v_mov_b32_e32 v17, v2
	v_lshlrev_b64 v[16:17], 12, v[16:17]
	v_lshl_add_u64 v[16:17], v[8:9], 0, v[16:17]
	flat_load_dword v45, v[16:17] nt
	v_or_b32_e32 v16, 58, v6
	v_mov_b32_e32 v17, v2
	v_lshlrev_b64 v[16:17], 12, v[16:17]
	v_lshl_add_u64 v[16:17], v[8:9], 0, v[16:17]
	flat_load_dword v46, v[16:17] nt
	v_or_b32_e32 v16, 60, v6
	v_mov_b32_e32 v17, v2
	v_or_b32_e32 v6, 62, v6
	v_lshlrev_b64 v[16:17], 12, v[16:17]
	v_lshlrev_b64 v[6:7], 12, v[6:7]
	v_lshl_add_u64 v[16:17], v[8:9], 0, v[16:17]
	v_lshl_add_u64 v[6:7], v[8:9], 0, v[6:7]
	flat_load_dword v16, v[16:17] nt
	s_lshl_b64 s[16:17], s[88:89], 1
	flat_load_dword v6, v[6:7] nt
	v_add_u32_e32 v7, 0x400, v5
	s_waitcnt vmcnt(0) lgkmcnt(0)
	ds_write2_b32 v5, v15, v18 offset1:66
	ds_write2_b32 v5, v19, v20 offset0:132 offset1:198
	ds_write2_b32 v7, v21, v22 offset0:8 offset1:74
	ds_write2_b32 v7, v23, v24 offset0:140 offset1:206
	v_add_u32_e32 v7, 0x800, v5
	ds_write2_b32 v7, v25, v26 offset0:16 offset1:82
	ds_write2_b32 v7, v27, v28 offset0:148 offset1:214
	v_add_u32_e32 v7, 0xc00, v5
	ds_write2_b32 v7, v29, v30 offset0:24 offset1:90
	ds_write2_b32 v7, v31, v32 offset0:156 offset1:222
	v_add_u32_e32 v7, 0x1000, v5
	ds_write2_b32 v7, v33, v34 offset0:32 offset1:98
	ds_write2_b32 v7, v35, v36 offset0:164 offset1:230
	v_add_u32_e32 v7, 0x1400, v5
	ds_write2_b32 v7, v37, v38 offset0:40 offset1:106
	ds_write2_b32 v7, v39, v40 offset0:172 offset1:238
	v_add_u32_e32 v7, 0x1800, v5
	ds_write2_b32 v7, v41, v42 offset0:48 offset1:114
	ds_write2_b32 v7, v43, v44 offset0:180 offset1:246
	v_add_u32_e32 v7, 0x1c00, v5
	ds_write2_b32 v7, v45, v46 offset0:56 offset1:122
	ds_write2_b32 v7, v16, v6 offset0:188 offset1:254
	s_add_u32 s2, s2, s16
	s_waitcnt lgkmcnt(0)
	s_addc_u32 s3, s3, s17
	v_lshlrev_b32_e32 v6, 1, v4
	v_mov_b32_e32 v7, v2
	v_lshl_add_u64 v[16:17], s[2:3], 0, v[6:7]
	ds_read2_b32 v[96:97], v11 offset1:33
	ds_read2_b32 v[98:99], v11 offset0:66 offset1:99
	ds_read2_b32 v[100:101], v11 offset0:132 offset1:165
	ds_read2_b32 v[102:103], v11 offset0:198 offset1:231
	ds_read2_b32 v[104:105], v11 offset0:8 offset1:41
	ds_read2_b32 v[106:107], v11 offset0:74 offset1:107
	ds_read2_b32 v[108:109], v11 offset0:140 offset1:173
	ds_read2_b32 v[110:111], v11 offset0:206 offset1:239
	ds_read2_b32 v[112:113], v11 offset0:16 offset1:49
	ds_read2_b32 v[114:115], v11 offset0:82 offset1:115
	ds_read2_b32 v[116:117], v11 offset0:148 offset1:181
	ds_read2_b32 v[118:119], v11 offset0:214 offset1:247
	ds_read2_b32 v[120:121], v11 offset0:24 offset1:57
	ds_read2_b32 v[122:123], v11 offset0:90 offset1:123
	ds_read2_b32 v[124:125], v11 offset0:156 offset1:189
	s_waitcnt lgkmcnt(7)
	ds_read2_b32 v[126:127], v11 offset0:222 offset1:255
	v_cvt_pk_bf16_f32 v6, v96, v97
	v_cvt_pk_bf16_f32 v7, v98, v99
	v_cvt_pk_bf16_f32 v8, v100, v101
	v_or_b32_e32 v15, s1, v10
	v_cvt_pk_bf16_f32 v9, v102, v103
	v_lshlrev_b32_e32 v18, 11, v15
	v_mov_b32_e32 v19, v2
	v_lshl_add_u64 v[18:19], v[16:17], 0, v[18:19]
	global_store_dwordx4 v[18:19], v[6:9], off
	s_nop 1
	v_or_b32_e32 v15, s1, v12
	v_cvt_pk_bf16_f32 v6, v104, v105
	v_cvt_pk_bf16_f32 v7, v106, v107
	v_cvt_pk_bf16_f32 v8, v108, v109
	v_cvt_pk_bf16_f32 v9, v110, v111
	v_lshlrev_b32_e32 v18, 11, v15
	v_mov_b32_e32 v19, v2
	v_lshl_add_u64 v[18:19], v[16:17], 0, v[18:19]
	global_store_dwordx4 v[18:19], v[6:9], off
	s_nop 1
	s_waitcnt lgkmcnt(0)
	v_or_b32_e32 v15, s1, v13
	v_cvt_pk_bf16_f32 v6, v112, v113
	v_cvt_pk_bf16_f32 v7, v114, v115
	v_cvt_pk_bf16_f32 v8, v116, v117
	v_cvt_pk_bf16_f32 v9, v118, v119
	v_lshlrev_b32_e32 v18, 11, v15
	v_mov_b32_e32 v19, v2
	v_lshl_add_u64 v[18:19], v[16:17], 0, v[18:19]
	global_store_dwordx4 v[18:19], v[6:9], off
	s_nop 1
	v_or_b32_e32 v15, s1, v14
	v_cvt_pk_bf16_f32 v6, v120, v121
	v_cvt_pk_bf16_f32 v7, v122, v123
	v_cvt_pk_bf16_f32 v8, v124, v125
	v_cvt_pk_bf16_f32 v9, v126, v127
	v_lshlrev_b32_e32 v18, 11, v15
	v_mov_b32_e32 v19, v2
	v_lshl_add_u64 v[16:17], v[16:17], 0, v[18:19]
	global_store_dwordx4 v[16:17], v[6:9], off
	s_waitcnt lgkmcnt(0)

.LBB0_811:
	s_andn2_b64 vcc, exec, s[2:3]
	s_cbranch_vccnz .LBB0_813
	v_readlane_b32 s1, v252, 6
	v_lshlrev_b32_e32 v8, 2, v0
	v_mov_b32_e32 v9, v2
	v_mov_b32_e32 v6, s1
	ds_read_b64 v[6:7], v6
	s_ashr_i32 s1, s0, 31
	s_lshl_b64 s[2:3], s[0:1], 20
	s_waitcnt lgkmcnt(0)
	v_readfirstlane_b32 s16, v6
	v_readfirstlane_b32 s17, v7
	s_add_u32 s16, s16, s2
	s_addc_u32 s17, s17, s3
	s_lshl_b64 s[2:3], s[0:1], 21
	s_add_u32 s2, s62, s2
	s_mul_i32 s1, s0, 0xffffc100
	s_addc_u32 s3, s63, s3
	s_add_i32 s1, s12, s1
	s_and_b32 s1, s1, 0x1fc0
	s_add_i32 s88, s1, 0xffffe700
	s_and_b32 s1, s14, 0x3e0
	s_lshl_b32 s18, s1, 2
	s_add_u32 s16, s16, s18
	v_or_b32_e32 v6, s88, v1
	s_addc_u32 s17, s17, 0
	v_mov_b32_e32 v7, v2
	v_lshl_add_u64 v[8:9], s[16:17], 0, v[8:9]
	v_lshlrev_b64 v[16:17], 12, v[6:7]
	v_lshl_add_u64 v[16:17], v[8:9], 0, v[16:17]
	flat_load_dword v15, v[16:17] nt
	v_or_b32_e32 v16, 2, v6
	v_mov_b32_e32 v17, v2
	v_lshlrev_b64 v[16:17], 12, v[16:17]
	v_lshl_add_u64 v[16:17], v[8:9], 0, v[16:17]
	flat_load_dword v18, v[16:17] nt
	v_or_b32_e32 v16, 4, v6
	v_mov_b32_e32 v17, v2
	v_lshlrev_b64 v[16:17], 12, v[16:17]
	v_lshl_add_u64 v[16:17], v[8:9], 0, v[16:17]
	flat_load_dword v19, v[16:17] nt
	v_or_b32_e32 v16, 6, v6
	v_mov_b32_e32 v17, v2
	v_lshlrev_b64 v[16:17], 12, v[16:17]
	v_lshl_add_u64 v[16:17], v[8:9], 0, v[16:17]
	flat_load_dword v20, v[16:17] nt
	v_or_b32_e32 v16, 8, v6
	v_mov_b32_e32 v17, v2
	v_lshlrev_b64 v[16:17], 12, v[16:17]
	v_lshl_add_u64 v[16:17], v[8:9], 0, v[16:17]
	flat_load_dword v21, v[16:17] nt
	v_or_b32_e32 v16, 10, v6
	v_mov_b32_e32 v17, v2
	v_lshlrev_b64 v[16:17], 12, v[16:17]
	v_lshl_add_u64 v[16:17], v[8:9], 0, v[16:17]
	flat_load_dword v22, v[16:17] nt
	v_or_b32_e32 v16, 12, v6
	v_mov_b32_e32 v17, v2
	v_lshlrev_b64 v[16:17], 12, v[16:17]
	v_lshl_add_u64 v[16:17], v[8:9], 0, v[16:17]
	flat_load_dword v23, v[16:17] nt
	v_or_b32_e32 v16, 14, v6
	v_mov_b32_e32 v17, v2
	v_lshlrev_b64 v[16:17], 12, v[16:17]
	v_lshl_add_u64 v[16:17], v[8:9], 0, v[16:17]
	flat_load_dword v24, v[16:17] nt
	v_or_b32_e32 v16, 16, v6
	v_mov_b32_e32 v17, v2
	v_lshlrev_b64 v[16:17], 12, v[16:17]
	v_lshl_add_u64 v[16:17], v[8:9], 0, v[16:17]
	flat_load_dword v25, v[16:17] nt
	v_or_b32_e32 v16, 18, v6
	v_mov_b32_e32 v17, v2
	v_lshlrev_b64 v[16:17], 12, v[16:17]
	v_lshl_add_u64 v[16:17], v[8:9], 0, v[16:17]
	flat_load_dword v26, v[16:17] nt
	v_or_b32_e32 v16, 20, v6
	v_mov_b32_e32 v17, v2
	v_lshlrev_b64 v[16:17], 12, v[16:17]
	v_lshl_add_u64 v[16:17], v[8:9], 0, v[16:17]
	flat_load_dword v27, v[16:17] nt
	v_or_b32_e32 v16, 22, v6
	v_mov_b32_e32 v17, v2
	v_lshlrev_b64 v[16:17], 12, v[16:17]
	v_lshl_add_u64 v[16:17], v[8:9], 0, v[16:17]
	flat_load_dword v28, v[16:17] nt
	v_or_b32_e32 v16, 24, v6
	v_mov_b32_e32 v17, v2
	v_lshlrev_b64 v[16:17], 12, v[16:17]
	v_lshl_add_u64 v[16:17], v[8:9], 0, v[16:17]
	flat_load_dword v29, v[16:17] nt
	v_or_b32_e32 v16, 26, v6
	v_mov_b32_e32 v17, v2
	v_lshlrev_b64 v[16:17], 12, v[16:17]
	v_lshl_add_u64 v[16:17], v[8:9], 0, v[16:17]
	flat_load_dword v30, v[16:17] nt
	v_or_b32_e32 v16, 28, v6
	v_mov_b32_e32 v17, v2
	v_lshlrev_b64 v[16:17], 12, v[16:17]
	v_lshl_add_u64 v[16:17], v[8:9], 0, v[16:17]
	flat_load_dword v31, v[16:17] nt
	v_or_b32_e32 v16, 30, v6
	v_mov_b32_e32 v17, v2
	v_lshlrev_b64 v[16:17], 12, v[16:17]
	v_lshl_add_u64 v[16:17], v[8:9], 0, v[16:17]
	flat_load_dword v32, v[16:17] nt
	v_or_b32_e32 v16, 32, v6
	v_mov_b32_e32 v17, v2
	v_lshlrev_b64 v[16:17], 12, v[16:17]
	v_lshl_add_u64 v[16:17], v[8:9], 0, v[16:17]
	flat_load_dword v33, v[16:17] nt
	v_or_b32_e32 v16, 34, v6
	v_mov_b32_e32 v17, v2
	v_lshlrev_b64 v[16:17], 12, v[16:17]
	v_lshl_add_u64 v[16:17], v[8:9], 0, v[16:17]
	flat_load_dword v34, v[16:17] nt
	v_or_b32_e32 v16, 36, v6
	v_mov_b32_e32 v17, v2
	v_lshlrev_b64 v[16:17], 12, v[16:17]
	v_lshl_add_u64 v[16:17], v[8:9], 0, v[16:17]
	flat_load_dword v35, v[16:17] nt
	v_or_b32_e32 v16, 38, v6
	v_mov_b32_e32 v17, v2
	v_lshlrev_b64 v[16:17], 12, v[16:17]
	v_lshl_add_u64 v[16:17], v[8:9], 0, v[16:17]
	flat_load_dword v36, v[16:17] nt
	v_or_b32_e32 v16, 40, v6
	v_mov_b32_e32 v17, v2
	v_lshlrev_b64 v[16:17], 12, v[16:17]
	v_lshl_add_u64 v[16:17], v[8:9], 0, v[16:17]
	flat_load_dword v37, v[16:17] nt
	v_or_b32_e32 v16, 42, v6
	v_mov_b32_e32 v17, v2
	v_lshlrev_b64 v[16:17], 12, v[16:17]
	v_lshl_add_u64 v[16:17], v[8:9], 0, v[16:17]
	flat_load_dword v38, v[16:17] nt
	v_or_b32_e32 v16, 44, v6
	v_mov_b32_e32 v17, v2
	v_lshlrev_b64 v[16:17], 12, v[16:17]
	v_lshl_add_u64 v[16:17], v[8:9], 0, v[16:17]
	flat_load_dword v39, v[16:17] nt
	v_or_b32_e32 v16, 46, v6
	v_mov_b32_e32 v17, v2
	v_lshlrev_b64 v[16:17], 12, v[16:17]
	v_lshl_add_u64 v[16:17], v[8:9], 0, v[16:17]
	flat_load_dword v40, v[16:17] nt
	v_or_b32_e32 v16, 48, v6
	v_mov_b32_e32 v17, v2
	v_lshlrev_b64 v[16:17], 12, v[16:17]
	v_lshl_add_u64 v[16:17], v[8:9], 0, v[16:17]
	flat_load_dword v41, v[16:17] nt
	v_or_b32_e32 v16, 50, v6
	v_mov_b32_e32 v17, v2
	v_lshlrev_b64 v[16:17], 12, v[16:17]
	v_lshl_add_u64 v[16:17], v[8:9], 0, v[16:17]
	flat_load_dword v42, v[16:17] nt
	v_or_b32_e32 v16, 52, v6
	v_mov_b32_e32 v17, v2
	v_lshlrev_b64 v[16:17], 12, v[16:17]
	v_lshl_add_u64 v[16:17], v[8:9], 0, v[16:17]
	flat_load_dword v43, v[16:17] nt
	v_or_b32_e32 v16, 54, v6
	v_mov_b32_e32 v17, v2
	v_lshlrev_b64 v[16:17], 12, v[16:17]
	v_lshl_add_u64 v[16:17], v[8:9], 0, v[16:17]
	flat_load_dword v44, v[16:17] nt
	v_or_b32_e32 v16, 56, v6
	v_mov_b32_e32 v17, v2
	v_lshlrev_b64 v[16:17], 12, v[16:17]
	v_lshl_add_u64 v[16:17], v[8:9], 0, v[16:17]
	flat_load_dword v45, v[16:17] nt
	v_or_b32_e32 v16, 58, v6
	v_mov_b32_e32 v17, v2
	v_lshlrev_b64 v[16:17], 12, v[16:17]
	v_lshl_add_u64 v[16:17], v[8:9], 0, v[16:17]
	flat_load_dword v46, v[16:17] nt
	v_or_b32_e32 v16, 60, v6
	v_mov_b32_e32 v17, v2
	v_or_b32_e32 v6, 62, v6
	v_lshlrev_b64 v[16:17], 12, v[16:17]
	v_lshlrev_b64 v[6:7], 12, v[6:7]
	v_lshl_add_u64 v[16:17], v[8:9], 0, v[16:17]
	v_lshl_add_u64 v[6:7], v[8:9], 0, v[6:7]
	flat_load_dword v16, v[16:17] nt
	s_lshl_b64 s[16:17], s[88:89], 1
	flat_load_dword v6, v[6:7] nt
	v_add_u32_e32 v7, 0x400, v5
	s_waitcnt vmcnt(0) lgkmcnt(0)
	ds_write2_b32 v5, v15, v18 offset1:66
	ds_write2_b32 v5, v19, v20 offset0:132 offset1:198
	ds_write2_b32 v7, v21, v22 offset0:8 offset1:74
	ds_write2_b32 v7, v23, v24 offset0:140 offset1:206
	v_add_u32_e32 v7, 0x800, v5
	ds_write2_b32 v7, v25, v26 offset0:16 offset1:82
	ds_write2_b32 v7, v27, v28 offset0:148 offset1:214
	v_add_u32_e32 v7, 0xc00, v5
	ds_write2_b32 v7, v29, v30 offset0:24 offset1:90
	ds_write2_b32 v7, v31, v32 offset0:156 offset1:222
	v_add_u32_e32 v7, 0x1000, v5
	ds_write2_b32 v7, v33, v34 offset0:32 offset1:98
	ds_write2_b32 v7, v35, v36 offset0:164 offset1:230
	v_add_u32_e32 v7, 0x1400, v5
	ds_write2_b32 v7, v37, v38 offset0:40 offset1:106
	ds_write2_b32 v7, v39, v40 offset0:172 offset1:238
	v_add_u32_e32 v7, 0x1800, v5
	ds_write2_b32 v7, v41, v42 offset0:48 offset1:114
	ds_write2_b32 v7, v43, v44 offset0:180 offset1:246
	v_add_u32_e32 v7, 0x1c00, v5
	ds_write2_b32 v7, v45, v46 offset0:56 offset1:122
	ds_write2_b32 v7, v16, v6 offset0:188 offset1:254
	s_waitcnt lgkmcnt(0)
	ds_read2_b32 v[96:97], v11 offset1:33
	ds_read2_b32 v[98:99], v11 offset0:66 offset1:99
	ds_read2_b32 v[100:101], v11 offset0:132 offset1:165
	ds_read2_b32 v[102:103], v11 offset0:198 offset1:231
	ds_read2_b32 v[104:105], v11 offset0:8 offset1:41
	ds_read2_b32 v[106:107], v11 offset0:74 offset1:107
	ds_read2_b32 v[108:109], v11 offset0:140 offset1:173
	ds_read2_b32 v[110:111], v11 offset0:206 offset1:239
	ds_read2_b32 v[112:113], v11 offset0:16 offset1:49
	ds_read2_b32 v[114:115], v11 offset0:82 offset1:115
	ds_read2_b32 v[116:117], v11 offset0:148 offset1:181
	ds_read2_b32 v[118:119], v11 offset0:214 offset1:247
	ds_read2_b32 v[120:121], v11 offset0:24 offset1:57
	ds_read2_b32 v[122:123], v11 offset0:90 offset1:123
	ds_read2_b32 v[124:125], v11 offset0:156 offset1:189
	s_waitcnt lgkmcnt(7)
	ds_read2_b32 v[126:127], v11 offset0:222 offset1:255
	v_cvt_pk_bf16_f32 v16, v96, v97
	s_add_u32 s2, s2, s16
	v_cvt_pk_bf16_f32 v17, v98, v99
	s_addc_u32 s3, s3, s17
	v_lshlrev_b32_e32 v6, 1, v4
	v_mov_b32_e32 v7, v2
	v_cvt_pk_bf16_f32 v18, v100, v101
	v_lshl_add_u64 v[6:7], s[2:3], 0, v[6:7]
	s_mov_b64 s[2:3], 0x5e00600
	v_cvt_pk_bf16_f32 v19, v102, v103
	v_or_b32_e32 v8, s1, v10
	v_lshl_add_u64 v[6:7], v[6:7], 0, s[2:3]
	v_lshlrev_b32_e32 v8, 11, v8
	v_mov_b32_e32 v9, v2
	v_lshl_add_u64 v[8:9], v[6:7], 0, v[8:9]
	global_store_dwordx4 v[8:9], v[16:19], off
	s_nop 1
	v_cvt_pk_bf16_f32 v16, v104, v105
	v_cvt_pk_bf16_f32 v17, v106, v107
	v_cvt_pk_bf16_f32 v18, v108, v109
	v_cvt_pk_bf16_f32 v19, v110, v111
	v_or_b32_e32 v8, s1, v12
	v_lshlrev_b32_e32 v8, 11, v8
	v_mov_b32_e32 v9, v2
	v_lshl_add_u64 v[8:9], v[6:7], 0, v[8:9]
	global_store_dwordx4 v[8:9], v[16:19], off
	s_nop 1
	s_waitcnt lgkmcnt(0)
	v_cvt_pk_bf16_f32 v16, v112, v113
	v_cvt_pk_bf16_f32 v17, v114, v115
	v_cvt_pk_bf16_f32 v18, v116, v117
	v_cvt_pk_bf16_f32 v19, v118, v119
	v_or_b32_e32 v8, s1, v13
	v_lshlrev_b32_e32 v8, 11, v8
	v_mov_b32_e32 v9, v2
	v_lshl_add_u64 v[8:9], v[6:7], 0, v[8:9]
	global_store_dwordx4 v[8:9], v[16:19], off
	s_nop 1
	v_cvt_pk_bf16_f32 v16, v120, v121
	v_cvt_pk_bf16_f32 v17, v122, v123
	v_cvt_pk_bf16_f32 v18, v124, v125
	v_cvt_pk_bf16_f32 v19, v126, v127
	v_or_b32_e32 v8, s1, v14
	v_lshlrev_b32_e32 v8, 11, v8
	v_mov_b32_e32 v9, v2
	v_lshl_add_u64 v[6:7], v[6:7], 0, v[8:9]
	global_store_dwordx4 v[6:7], v[16:19], off
	s_waitcnt lgkmcnt(0)

.LBB0_814:
	s_andn2_b64 vcc, exec, s[2:3]
	s_cbranch_vccnz .LBB0_816
	v_readlane_b32 s1, v252, 7
	v_lshlrev_b32_e32 v8, 2, v0
	v_mov_b32_e32 v9, v2
	v_mov_b32_e32 v6, s1
	ds_read_b64 v[6:7], v6
	s_ashr_i32 s1, s0, 31
	s_lshl_b64 s[2:3], s[0:1], 21
	s_mul_i32 s1, s0, 0xffffc100
	s_waitcnt lgkmcnt(0)
	v_readfirstlane_b32 s16, v6
	v_readfirstlane_b32 s17, v7
	s_add_u32 s16, s16, s2
	s_addc_u32 s17, s17, s3
	s_add_u32 s2, s94, s2
	s_addc_u32 s3, s24, s3
	s_add_i32 s1, s12, s1
	s_and_b32 s1, s1, 0x1fc0
	s_add_i32 s88, s1, 0xffffe900
	s_and_b32 s1, s14, 0x3e0
	s_lshl_b32 s18, s1, 2
	s_add_u32 s16, s16, s18
	v_or_b32_e32 v6, s88, v1
	s_addc_u32 s17, s17, 0
	v_mov_b32_e32 v7, v2
	v_lshl_add_u64 v[8:9], s[16:17], 0, v[8:9]
	v_lshlrev_b64 v[16:17], 12, v[6:7]
	v_lshl_add_u64 v[16:17], v[8:9], 0, v[16:17]
	flat_load_dword v15, v[16:17] nt
	v_or_b32_e32 v16, 2, v6
	v_mov_b32_e32 v17, v2
	v_lshlrev_b64 v[16:17], 12, v[16:17]
	v_lshl_add_u64 v[16:17], v[8:9], 0, v[16:17]
	flat_load_dword v18, v[16:17] nt
	v_or_b32_e32 v16, 4, v6
	v_mov_b32_e32 v17, v2
	v_lshlrev_b64 v[16:17], 12, v[16:17]
	v_lshl_add_u64 v[16:17], v[8:9], 0, v[16:17]
	flat_load_dword v19, v[16:17] nt
	v_or_b32_e32 v16, 6, v6
	v_mov_b32_e32 v17, v2
	v_lshlrev_b64 v[16:17], 12, v[16:17]
	v_lshl_add_u64 v[16:17], v[8:9], 0, v[16:17]
	flat_load_dword v20, v[16:17] nt
	v_or_b32_e32 v16, 8, v6
	v_mov_b32_e32 v17, v2
	v_lshlrev_b64 v[16:17], 12, v[16:17]
	v_lshl_add_u64 v[16:17], v[8:9], 0, v[16:17]
	flat_load_dword v21, v[16:17] nt
	v_or_b32_e32 v16, 10, v6
	v_mov_b32_e32 v17, v2
	v_lshlrev_b64 v[16:17], 12, v[16:17]
	v_lshl_add_u64 v[16:17], v[8:9], 0, v[16:17]
	flat_load_dword v22, v[16:17] nt
	v_or_b32_e32 v16, 12, v6
	v_mov_b32_e32 v17, v2
	v_lshlrev_b64 v[16:17], 12, v[16:17]
	v_lshl_add_u64 v[16:17], v[8:9], 0, v[16:17]
	flat_load_dword v23, v[16:17] nt
	v_or_b32_e32 v16, 14, v6
	v_mov_b32_e32 v17, v2
	v_lshlrev_b64 v[16:17], 12, v[16:17]
	v_lshl_add_u64 v[16:17], v[8:9], 0, v[16:17]
	flat_load_dword v24, v[16:17] nt
	v_or_b32_e32 v16, 16, v6
	v_mov_b32_e32 v17, v2
	v_lshlrev_b64 v[16:17], 12, v[16:17]
	v_lshl_add_u64 v[16:17], v[8:9], 0, v[16:17]
	flat_load_dword v25, v[16:17] nt
	v_or_b32_e32 v16, 18, v6
	v_mov_b32_e32 v17, v2
	v_lshlrev_b64 v[16:17], 12, v[16:17]
	v_lshl_add_u64 v[16:17], v[8:9], 0, v[16:17]
	flat_load_dword v26, v[16:17] nt
	v_or_b32_e32 v16, 20, v6
	v_mov_b32_e32 v17, v2
	v_lshlrev_b64 v[16:17], 12, v[16:17]
	v_lshl_add_u64 v[16:17], v[8:9], 0, v[16:17]
	flat_load_dword v27, v[16:17] nt
	v_or_b32_e32 v16, 22, v6
	v_mov_b32_e32 v17, v2
	v_lshlrev_b64 v[16:17], 12, v[16:17]
	v_lshl_add_u64 v[16:17], v[8:9], 0, v[16:17]
	flat_load_dword v28, v[16:17] nt
	v_or_b32_e32 v16, 24, v6
	v_mov_b32_e32 v17, v2
	v_lshlrev_b64 v[16:17], 12, v[16:17]
	v_lshl_add_u64 v[16:17], v[8:9], 0, v[16:17]
	flat_load_dword v29, v[16:17] nt
	v_or_b32_e32 v16, 26, v6
	v_mov_b32_e32 v17, v2
	v_lshlrev_b64 v[16:17], 12, v[16:17]
	v_lshl_add_u64 v[16:17], v[8:9], 0, v[16:17]
	flat_load_dword v30, v[16:17] nt
	v_or_b32_e32 v16, 28, v6
	v_mov_b32_e32 v17, v2
	v_lshlrev_b64 v[16:17], 12, v[16:17]
	v_lshl_add_u64 v[16:17], v[8:9], 0, v[16:17]
	flat_load_dword v31, v[16:17] nt
	v_or_b32_e32 v16, 30, v6
	v_mov_b32_e32 v17, v2
	v_lshlrev_b64 v[16:17], 12, v[16:17]
	v_lshl_add_u64 v[16:17], v[8:9], 0, v[16:17]
	flat_load_dword v32, v[16:17] nt
	v_or_b32_e32 v16, 32, v6
	v_mov_b32_e32 v17, v2
	v_lshlrev_b64 v[16:17], 12, v[16:17]
	v_lshl_add_u64 v[16:17], v[8:9], 0, v[16:17]
	flat_load_dword v33, v[16:17] nt
	v_or_b32_e32 v16, 34, v6
	v_mov_b32_e32 v17, v2
	v_lshlrev_b64 v[16:17], 12, v[16:17]
	v_lshl_add_u64 v[16:17], v[8:9], 0, v[16:17]
	flat_load_dword v34, v[16:17] nt
	v_or_b32_e32 v16, 36, v6
	v_mov_b32_e32 v17, v2
	v_lshlrev_b64 v[16:17], 12, v[16:17]
	v_lshl_add_u64 v[16:17], v[8:9], 0, v[16:17]
	flat_load_dword v35, v[16:17] nt
	v_or_b32_e32 v16, 38, v6
	v_mov_b32_e32 v17, v2
	v_lshlrev_b64 v[16:17], 12, v[16:17]
	v_lshl_add_u64 v[16:17], v[8:9], 0, v[16:17]
	flat_load_dword v36, v[16:17] nt
	v_or_b32_e32 v16, 40, v6
	v_mov_b32_e32 v17, v2
	v_lshlrev_b64 v[16:17], 12, v[16:17]
	v_lshl_add_u64 v[16:17], v[8:9], 0, v[16:17]
	flat_load_dword v37, v[16:17] nt
	v_or_b32_e32 v16, 42, v6
	v_mov_b32_e32 v17, v2
	v_lshlrev_b64 v[16:17], 12, v[16:17]
	v_lshl_add_u64 v[16:17], v[8:9], 0, v[16:17]
	flat_load_dword v38, v[16:17] nt
	v_or_b32_e32 v16, 44, v6
	v_mov_b32_e32 v17, v2
	v_lshlrev_b64 v[16:17], 12, v[16:17]
	v_lshl_add_u64 v[16:17], v[8:9], 0, v[16:17]
	flat_load_dword v39, v[16:17] nt
	v_or_b32_e32 v16, 46, v6
	v_mov_b32_e32 v17, v2
	v_lshlrev_b64 v[16:17], 12, v[16:17]
	v_lshl_add_u64 v[16:17], v[8:9], 0, v[16:17]
	flat_load_dword v40, v[16:17] nt
	v_or_b32_e32 v16, 48, v6
	v_mov_b32_e32 v17, v2
	v_lshlrev_b64 v[16:17], 12, v[16:17]
	v_lshl_add_u64 v[16:17], v[8:9], 0, v[16:17]
	flat_load_dword v41, v[16:17] nt
	v_or_b32_e32 v16, 50, v6
	v_mov_b32_e32 v17, v2
	v_lshlrev_b64 v[16:17], 12, v[16:17]
	v_lshl_add_u64 v[16:17], v[8:9], 0, v[16:17]
	flat_load_dword v42, v[16:17] nt
	v_or_b32_e32 v16, 52, v6
	v_mov_b32_e32 v17, v2
	v_lshlrev_b64 v[16:17], 12, v[16:17]
	v_lshl_add_u64 v[16:17], v[8:9], 0, v[16:17]
	flat_load_dword v43, v[16:17] nt
	v_or_b32_e32 v16, 54, v6
	v_mov_b32_e32 v17, v2
	v_lshlrev_b64 v[16:17], 12, v[16:17]
	v_lshl_add_u64 v[16:17], v[8:9], 0, v[16:17]
	flat_load_dword v44, v[16:17] nt
	v_or_b32_e32 v16, 56, v6
	v_mov_b32_e32 v17, v2
	v_lshlrev_b64 v[16:17], 12, v[16:17]
	v_lshl_add_u64 v[16:17], v[8:9], 0, v[16:17]
	flat_load_dword v45, v[16:17] nt
	v_or_b32_e32 v16, 58, v6
	v_mov_b32_e32 v17, v2
	v_lshlrev_b64 v[16:17], 12, v[16:17]
	v_lshl_add_u64 v[16:17], v[8:9], 0, v[16:17]
	flat_load_dword v46, v[16:17] nt
	v_or_b32_e32 v16, 60, v6
	v_mov_b32_e32 v17, v2
	v_or_b32_e32 v6, 62, v6
	v_lshlrev_b64 v[16:17], 12, v[16:17]
	v_lshlrev_b64 v[6:7], 12, v[6:7]
	v_lshl_add_u64 v[16:17], v[8:9], 0, v[16:17]
	v_lshl_add_u64 v[6:7], v[8:9], 0, v[6:7]
	flat_load_dword v16, v[16:17] nt
	s_lshl_b64 s[16:17], s[88:89], 1
	flat_load_dword v6, v[6:7] nt
	v_add_u32_e32 v7, 0x400, v5
	s_waitcnt vmcnt(0) lgkmcnt(0)
	ds_write2_b32 v5, v15, v18 offset1:66
	ds_write2_b32 v5, v19, v20 offset0:132 offset1:198
	ds_write2_b32 v7, v21, v22 offset0:8 offset1:74
	ds_write2_b32 v7, v23, v24 offset0:140 offset1:206
	v_add_u32_e32 v7, 0x800, v5
	ds_write2_b32 v7, v25, v26 offset0:16 offset1:82
	ds_write2_b32 v7, v27, v28 offset0:148 offset1:214
	v_add_u32_e32 v7, 0xc00, v5
	ds_write2_b32 v7, v29, v30 offset0:24 offset1:90
	ds_write2_b32 v7, v31, v32 offset0:156 offset1:222
	v_add_u32_e32 v7, 0x1000, v5
	ds_write2_b32 v7, v33, v34 offset0:32 offset1:98
	ds_write2_b32 v7, v35, v36 offset0:164 offset1:230
	v_add_u32_e32 v7, 0x1400, v5
	ds_write2_b32 v7, v37, v38 offset0:40 offset1:106
	ds_write2_b32 v7, v39, v40 offset0:172 offset1:238
	v_add_u32_e32 v7, 0x1800, v5
	ds_write2_b32 v7, v41, v42 offset0:48 offset1:114
	ds_write2_b32 v7, v43, v44 offset0:180 offset1:246
	v_add_u32_e32 v7, 0x1c00, v5
	ds_write2_b32 v7, v45, v46 offset0:56 offset1:122
	ds_write2_b32 v7, v16, v6 offset0:188 offset1:254
	s_add_u32 s2, s2, s16
	s_waitcnt lgkmcnt(0)
	s_addc_u32 s3, s3, s17
	v_lshlrev_b32_e32 v6, 1, v4
	v_mov_b32_e32 v7, v2
	v_lshl_add_u64 v[16:17], s[2:3], 0, v[6:7]
	ds_read2_b32 v[96:97], v11 offset1:33
	ds_read2_b32 v[98:99], v11 offset0:66 offset1:99
	ds_read2_b32 v[100:101], v11 offset0:132 offset1:165
	ds_read2_b32 v[102:103], v11 offset0:198 offset1:231
	ds_read2_b32 v[104:105], v11 offset0:8 offset1:41
	ds_read2_b32 v[106:107], v11 offset0:74 offset1:107
	ds_read2_b32 v[108:109], v11 offset0:140 offset1:173
	ds_read2_b32 v[110:111], v11 offset0:206 offset1:239
	ds_read2_b32 v[112:113], v11 offset0:16 offset1:49
	ds_read2_b32 v[114:115], v11 offset0:82 offset1:115
	ds_read2_b32 v[116:117], v11 offset0:148 offset1:181
	ds_read2_b32 v[118:119], v11 offset0:214 offset1:247
	ds_read2_b32 v[120:121], v11 offset0:24 offset1:57
	ds_read2_b32 v[122:123], v11 offset0:90 offset1:123
	ds_read2_b32 v[124:125], v11 offset0:156 offset1:189
	s_waitcnt lgkmcnt(7)
	ds_read2_b32 v[126:127], v11 offset0:222 offset1:255
	v_cvt_pk_bf16_f32 v6, v96, v97
	v_cvt_pk_bf16_f32 v7, v98, v99
	v_cvt_pk_bf16_f32 v8, v100, v101
	v_or_b32_e32 v15, s1, v10
	v_cvt_pk_bf16_f32 v9, v102, v103
	v_lshlrev_b32_e32 v18, 11, v15
	v_mov_b32_e32 v19, v2
	v_lshl_add_u64 v[18:19], v[16:17], 0, v[18:19]
	global_store_dwordx4 v[18:19], v[6:9], off
	s_nop 1
	v_or_b32_e32 v15, s1, v12
	v_cvt_pk_bf16_f32 v6, v104, v105
	v_cvt_pk_bf16_f32 v7, v106, v107
	v_cvt_pk_bf16_f32 v8, v108, v109
	v_cvt_pk_bf16_f32 v9, v110, v111
	v_lshlrev_b32_e32 v18, 11, v15
	v_mov_b32_e32 v19, v2
	v_lshl_add_u64 v[18:19], v[16:17], 0, v[18:19]
	global_store_dwordx4 v[18:19], v[6:9], off
	s_nop 1
	s_waitcnt lgkmcnt(0)
	v_or_b32_e32 v15, s1, v13
	v_cvt_pk_bf16_f32 v6, v112, v113
	v_cvt_pk_bf16_f32 v7, v114, v115
	v_cvt_pk_bf16_f32 v8, v116, v117
	v_cvt_pk_bf16_f32 v9, v118, v119
	v_lshlrev_b32_e32 v18, 11, v15
	v_mov_b32_e32 v19, v2
	v_lshl_add_u64 v[18:19], v[16:17], 0, v[18:19]
	global_store_dwordx4 v[18:19], v[6:9], off
	s_nop 1
	v_or_b32_e32 v15, s1, v14
	v_cvt_pk_bf16_f32 v6, v120, v121
	v_cvt_pk_bf16_f32 v7, v122, v123
	v_cvt_pk_bf16_f32 v8, v124, v125
	v_cvt_pk_bf16_f32 v9, v126, v127
	v_lshlrev_b32_e32 v18, 11, v15
	v_mov_b32_e32 v19, v2
	v_lshl_add_u64 v[16:17], v[16:17], 0, v[18:19]
	global_store_dwordx4 v[16:17], v[6:9], off
	s_waitcnt lgkmcnt(0)

.LBB0_817:
	s_andn2_b64 vcc, exec, s[2:3]
	s_cbranch_vccnz .LBB0_819
	v_mov_b32_e32 v6, s21
	ds_read_b64 v[6:7], v6
	s_bfe_u32 s1, s15, 0xd0003
	s_mulk_i32 s1, 0x1643
	s_lshr_b32 s2, s1, 17
	s_mul_i32 s1, s2, 0xb8
	s_sub_i32 s1, s15, s1
	s_waitcnt lgkmcnt(0)
	v_readfirstlane_b32 s3, v6
	s_mul_i32 s18, s0, 0x1700000
	v_readfirstlane_b32 s16, v7
	s_mul_hi_i32 s17, s0, 0x1700000
	s_add_u32 s18, s3, s18
	s_addc_u32 s17, s16, s17
	s_mul_i32 s3, s0, 0xb80000
	s_mul_hi_i32 s16, s0, 0xb80000
	s_add_u32 s3, s25, s3
	s_addc_u32 s16, s26, s16
	s_lshl_b32 s1, s1, 5
	s_and_b32 s1, s1, 0xffe0
	s_lshl_b32 s19, s1, 2
	v_lshl_or_b32 v8, s2, 6, v1
	s_add_u32 s18, s18, s19
	s_addc_u32 s19, s17, 0
	v_lshlrev_b32_e32 v6, 2, v0
	v_mov_b32_e32 v7, v2
	v_mul_u32_u24_e32 v8, 0x1700, v8
	v_lshl_add_u64 v[6:7], s[18:19], 0, v[6:7]
	v_lshlrev_b32_e32 v8, 2, v8
	v_mov_b32_e32 v9, v2
	v_lshl_add_u64 v[6:7], v[6:7], 0, v[8:9]
	s_mov_b32 s17, 0xb000
	v_add_co_u32_e32 v8, vcc, s17, v6
	s_mov_b32 s17, 0x17000
	s_nop 0
	v_addc_co_u32_e32 v9, vcc, 0, v7, vcc
	flat_load_dword v16, v[8:9] offset:2048 nt
	v_add_co_u32_e32 v8, vcc, s17, v6
	s_mov_b32 s17, 0x22000
	s_nop 0
	v_addc_co_u32_e32 v9, vcc, 0, v7, vcc
	flat_load_dword v15, v[6:7] nt
	flat_load_dword v17, v[8:9] nt
	v_add_co_u32_e32 v8, vcc, s17, v6
	s_mov_b32 s17, 0x2e000
	s_nop 0
	v_addc_co_u32_e32 v9, vcc, 0, v7, vcc
	flat_load_dword v18, v[8:9] offset:2048 nt
	v_add_co_u32_e32 v8, vcc, s17, v6
	s_mov_b32 s17, 0x39000
	s_nop 0
	v_addc_co_u32_e32 v9, vcc, 0, v7, vcc
	flat_load_dword v19, v[8:9] nt
	v_add_co_u32_e32 v8, vcc, s17, v6
	s_mov_b32 s17, 0x45000
	s_nop 0
	v_addc_co_u32_e32 v9, vcc, 0, v7, vcc
	flat_load_dword v20, v[8:9] offset:2048 nt
	v_add_co_u32_e32 v8, vcc, s17, v6
	s_mov_b32 s17, 0x50000
	s_nop 0
	v_addc_co_u32_e32 v9, vcc, 0, v7, vcc
	flat_load_dword v21, v[8:9] nt
	v_add_co_u32_e32 v8, vcc, s17, v6
	s_mov_b32 s17, 0x5c000
	s_nop 0
	v_addc_co_u32_e32 v9, vcc, 0, v7, vcc
	flat_load_dword v22, v[8:9] offset:2048 nt
	v_add_co_u32_e32 v8, vcc, s17, v6
	s_mov_b32 s17, 0x67000
	s_nop 0
	v_addc_co_u32_e32 v9, vcc, 0, v7, vcc
	flat_load_dword v23, v[8:9] nt
	v_add_co_u32_e32 v8, vcc, s17, v6
	s_mov_b32 s17, 0x73000
	s_nop 0
	v_addc_co_u32_e32 v9, vcc, 0, v7, vcc
	flat_load_dword v24, v[8:9] offset:2048 nt
	v_add_co_u32_e32 v8, vcc, s17, v6
	s_mov_b32 s17, 0x7e000
	s_nop 0
	v_addc_co_u32_e32 v9, vcc, 0, v7, vcc
	flat_load_dword v25, v[8:9] nt
	v_add_co_u32_e32 v8, vcc, s17, v6
	s_mov_b32 s17, 0x8a000
	s_nop 0
	v_addc_co_u32_e32 v9, vcc, 0, v7, vcc
	flat_load_dword v26, v[8:9] offset:2048 nt
	v_add_co_u32_e32 v8, vcc, s17, v6
	s_mov_b32 s17, 0x95000
	s_nop 0
	v_addc_co_u32_e32 v9, vcc, 0, v7, vcc
	flat_load_dword v27, v[8:9] nt
	v_add_co_u32_e32 v8, vcc, s17, v6
	s_mov_b32 s17, 0xa1000
	s_nop 0
	v_addc_co_u32_e32 v9, vcc, 0, v7, vcc
	flat_load_dword v28, v[8:9] offset:2048 nt
	v_add_co_u32_e32 v8, vcc, s17, v6
	s_mov_b32 s17, 0xac000
	s_nop 0
	v_addc_co_u32_e32 v9, vcc, 0, v7, vcc
	flat_load_dword v29, v[8:9] nt
	v_add_co_u32_e32 v8, vcc, s17, v6
	s_mov_b32 s17, 0xb8000
	s_nop 0
	v_addc_co_u32_e32 v9, vcc, 0, v7, vcc
	flat_load_dword v30, v[8:9] offset:2048 nt
	v_add_co_u32_e32 v8, vcc, s17, v6
	s_mov_b32 s17, 0xc3000
	s_nop 0
	v_addc_co_u32_e32 v9, vcc, 0, v7, vcc
	flat_load_dword v31, v[8:9] nt
	v_add_co_u32_e32 v8, vcc, s17, v6
	s_mov_b32 s17, 0xcf000
	s_nop 0
	v_addc_co_u32_e32 v9, vcc, 0, v7, vcc
	flat_load_dword v32, v[8:9] offset:2048 nt
	v_add_co_u32_e32 v8, vcc, s17, v6
	s_mov_b32 s17, 0xda000
	s_nop 0
	v_addc_co_u32_e32 v9, vcc, 0, v7, vcc
	flat_load_dword v33, v[8:9] nt
	v_add_co_u32_e32 v8, vcc, s17, v6
	s_mov_b32 s17, 0xe6000
	s_nop 0
	v_addc_co_u32_e32 v9, vcc, 0, v7, vcc
	flat_load_dword v34, v[8:9] offset:2048 nt
	v_add_co_u32_e32 v8, vcc, s17, v6
	s_mov_b32 s17, 0xf1000
	s_nop 0
	v_addc_co_u32_e32 v9, vcc, 0, v7, vcc
	flat_load_dword v35, v[8:9] nt
	v_add_co_u32_e32 v8, vcc, s17, v6
	s_mov_b32 s17, 0xfd000
	s_nop 0
	v_addc_co_u32_e32 v9, vcc, 0, v7, vcc
	flat_load_dword v36, v[8:9] offset:2048 nt
	v_add_co_u32_e32 v8, vcc, s17, v6
	s_mov_b32 s17, 0x108000
	s_nop 0
	v_addc_co_u32_e32 v9, vcc, 0, v7, vcc
	flat_load_dword v37, v[8:9] nt
	v_add_co_u32_e32 v8, vcc, s17, v6
	s_mov_b32 s17, 0x114000
	s_nop 0
	v_addc_co_u32_e32 v9, vcc, 0, v7, vcc
	flat_load_dword v38, v[8:9] offset:2048 nt
	v_add_co_u32_e32 v8, vcc, s17, v6
	s_mov_b32 s17, 0x11f000
	s_nop 0
	v_addc_co_u32_e32 v9, vcc, 0, v7, vcc
	flat_load_dword v39, v[8:9] nt
	v_add_co_u32_e32 v8, vcc, s17, v6
	s_mov_b32 s17, 0x12b000
	s_nop 0
	v_addc_co_u32_e32 v9, vcc, 0, v7, vcc
	flat_load_dword v40, v[8:9] offset:2048 nt
	v_add_co_u32_e32 v8, vcc, s17, v6
	s_mov_b32 s17, 0x136000
	s_nop 0
	v_addc_co_u32_e32 v9, vcc, 0, v7, vcc
	flat_load_dword v41, v[8:9] nt
	v_add_co_u32_e32 v8, vcc, s17, v6
	s_mov_b32 s17, 0x142000
	s_nop 0
	v_addc_co_u32_e32 v9, vcc, 0, v7, vcc
	flat_load_dword v42, v[8:9] offset:2048 nt
	v_add_co_u32_e32 v8, vcc, s17, v6
	s_mov_b32 s17, 0x14d000
	s_nop 0
	v_addc_co_u32_e32 v9, vcc, 0, v7, vcc
	flat_load_dword v43, v[8:9] nt
	v_add_co_u32_e32 v8, vcc, s17, v6
	s_mov_b32 s17, 0x159000
	s_nop 0
	v_addc_co_u32_e32 v9, vcc, 0, v7, vcc
	flat_load_dword v44, v[8:9] offset:2048 nt
	v_add_co_u32_e32 v8, vcc, s17, v6
	s_mov_b32 s17, 0x164000
	s_nop 0
	v_addc_co_u32_e32 v9, vcc, 0, v7, vcc
	v_add_co_u32_e32 v6, vcc, s17, v6
	flat_load_dword v8, v[8:9] nt
	s_nop 0
	v_addc_co_u32_e32 v7, vcc, 0, v7, vcc
	flat_load_dword v6, v[6:7] offset:2048 nt
	v_add_u32_e32 v7, 0x400, v5
	s_waitcnt vmcnt(0) lgkmcnt(0)
	ds_write2_b32 v5, v15, v16 offset1:66
	ds_write2_b32 v5, v17, v18 offset0:132 offset1:198
	ds_write2_b32 v7, v19, v20 offset0:8 offset1:74
	ds_write2_b32 v7, v21, v22 offset0:140 offset1:206
	v_add_u32_e32 v7, 0x800, v5
	ds_write2_b32 v7, v23, v24 offset0:16 offset1:82
	ds_write2_b32 v7, v25, v26 offset0:148 offset1:214
	v_add_u32_e32 v7, 0xc00, v5
	ds_write2_b32 v7, v27, v28 offset0:24 offset1:90
	ds_write2_b32 v7, v29, v30 offset0:156 offset1:222
	v_add_u32_e32 v7, 0x1000, v5
	ds_write2_b32 v7, v31, v32 offset0:32 offset1:98
	ds_write2_b32 v7, v33, v34 offset0:164 offset1:230
	v_add_u32_e32 v7, 0x1400, v5
	ds_write2_b32 v7, v35, v36 offset0:40 offset1:106
	ds_write2_b32 v7, v37, v38 offset0:172 offset1:238
	v_add_u32_e32 v7, 0x1800, v5
	ds_write2_b32 v7, v39, v40 offset0:48 offset1:114
	ds_write2_b32 v7, v41, v42 offset0:180 offset1:246
	v_add_u32_e32 v7, 0x1c00, v5
	s_lshl_b32 s2, s2, 7
	ds_write2_b32 v7, v43, v44 offset0:56 offset1:122
	ds_write2_b32 v7, v8, v6 offset0:188 offset1:254
	s_add_u32 s2, s3, s2
	s_waitcnt lgkmcnt(0)
	s_addc_u32 s3, s16, 0
	v_lshlrev_b32_e32 v6, 1, v4
	v_mov_b32_e32 v7, v2
	v_lshl_add_u64 v[16:17], s[2:3], 0, v[6:7]
	ds_read2_b32 v[96:97], v11 offset1:33
	ds_read2_b32 v[98:99], v11 offset0:66 offset1:99
	ds_read2_b32 v[100:101], v11 offset0:132 offset1:165
	ds_read2_b32 v[102:103], v11 offset0:198 offset1:231
	ds_read2_b32 v[104:105], v11 offset0:8 offset1:41
	ds_read2_b32 v[106:107], v11 offset0:74 offset1:107
	ds_read2_b32 v[108:109], v11 offset0:140 offset1:173
	ds_read2_b32 v[110:111], v11 offset0:206 offset1:239
	ds_read2_b32 v[112:113], v11 offset0:16 offset1:49
	ds_read2_b32 v[114:115], v11 offset0:82 offset1:115
	ds_read2_b32 v[116:117], v11 offset0:148 offset1:181
	ds_read2_b32 v[118:119], v11 offset0:214 offset1:247
	ds_read2_b32 v[120:121], v11 offset0:24 offset1:57
	ds_read2_b32 v[122:123], v11 offset0:90 offset1:123
	ds_read2_b32 v[124:125], v11 offset0:156 offset1:189
	s_waitcnt lgkmcnt(7)
	ds_read2_b32 v[126:127], v11 offset0:222 offset1:255
	v_cvt_pk_bf16_f32 v6, v96, v97
	v_cvt_pk_bf16_f32 v7, v98, v99
	v_cvt_pk_bf16_f32 v8, v100, v101
	v_or_b32_e32 v15, s1, v10
	v_cvt_pk_bf16_f32 v9, v102, v103
	v_lshlrev_b32_e32 v18, 11, v15
	v_mov_b32_e32 v19, v2
	v_lshl_add_u64 v[18:19], v[16:17], 0, v[18:19]
	global_store_dwordx4 v[18:19], v[6:9], off
	s_nop 1
	v_or_b32_e32 v15, s1, v12
	v_cvt_pk_bf16_f32 v6, v104, v105
	v_cvt_pk_bf16_f32 v7, v106, v107
	v_cvt_pk_bf16_f32 v8, v108, v109
	v_cvt_pk_bf16_f32 v9, v110, v111
	v_lshlrev_b32_e32 v18, 11, v15
	v_mov_b32_e32 v19, v2
	v_lshl_add_u64 v[18:19], v[16:17], 0, v[18:19]
	global_store_dwordx4 v[18:19], v[6:9], off
	s_nop 1
	s_waitcnt lgkmcnt(0)
	v_or_b32_e32 v15, s1, v13
	v_cvt_pk_bf16_f32 v6, v112, v113
	v_cvt_pk_bf16_f32 v7, v114, v115
	v_cvt_pk_bf16_f32 v8, v116, v117
	v_cvt_pk_bf16_f32 v9, v118, v119
	v_lshlrev_b32_e32 v18, 11, v15
	v_mov_b32_e32 v19, v2
	v_lshl_add_u64 v[18:19], v[16:17], 0, v[18:19]
	global_store_dwordx4 v[18:19], v[6:9], off
	s_nop 1
	v_or_b32_e32 v15, s1, v14
	v_cvt_pk_bf16_f32 v6, v120, v121
	v_cvt_pk_bf16_f32 v7, v122, v123
	v_cvt_pk_bf16_f32 v8, v124, v125
	v_cvt_pk_bf16_f32 v9, v126, v127
	v_lshlrev_b32_e32 v18, 11, v15
	v_mov_b32_e32 v19, v2
	v_lshl_add_u64 v[16:17], v[16:17], 0, v[18:19]
	global_store_dwordx4 v[16:17], v[6:9], off
	s_waitcnt lgkmcnt(0)
	s_mov_b32 s19, s69

.LBB0_820:
	s_andn2_b64 vcc, exec, s[2:3]
	s_cbranch_vccnz .LBB0_797
	v_mov_b32_e32 v6, s33
	s_addk_i32 s15, 0xc00
	ds_read_b64 v[6:7], v6
	s_mul_hi_i32 s1, s15, 0x2aaaaaab
	s_lshr_b32 s2, s1, 31
	s_ashr_i32 s1, s1, 5
	s_add_i32 s1, s1, s2
	s_mul_i32 s2, s1, 0xc0
	s_sub_i32 s3, s15, s2
	s_waitcnt lgkmcnt(0)
	v_readfirstlane_b32 s2, v6
	s_mul_i32 s17, s0, 0x1800000
	v_readfirstlane_b32 s15, v7
	s_mul_hi_i32 s16, s0, 0x1800000
	s_add_u32 s17, s2, s17
	s_addc_u32 s22, s15, s16
	s_mul_hi_i32 s2, s0, 0xc00000
	s_mul_i32 s0, s0, 0xc00000
	s_add_u32 s15, s62, s0
	s_addc_u32 s16, s63, s2
	s_lshl_b32 s0, s3, 5
	s_lshl_b32 s2, s1, 6
	s_ashr_i32 s1, s0, 31
	s_lshl_b64 s[18:19], s[0:1], 2
	s_add_u32 s18, s17, s18
	s_addc_u32 s19, s22, s19
	v_lshlrev_b32_e32 v6, 2, v0
	v_mov_b32_e32 v7, v2
	v_or_b32_e32 v15, s2, v1
	v_lshl_add_u64 v[6:7], s[18:19], 0, v[6:7]
	v_mad_i64_i32 v[8:9], s[18:19], v15, s67, v[6:7]
	flat_load_dword v16, v[8:9] nt
	v_or_b32_e32 v8, 2, v15
	v_mad_i64_i32 v[8:9], s[18:19], v8, s67, v[6:7]
	flat_load_dword v17, v[8:9] nt
	v_or_b32_e32 v8, 4, v15
	v_mad_i64_i32 v[8:9], s[18:19], v8, s67, v[6:7]
	flat_load_dword v18, v[8:9] nt
	v_or_b32_e32 v8, 6, v15
	v_mad_i64_i32 v[8:9], s[18:19], v8, s67, v[6:7]
	flat_load_dword v19, v[8:9] nt
	v_or_b32_e32 v8, 8, v15
	v_mad_i64_i32 v[8:9], s[18:19], v8, s67, v[6:7]
	flat_load_dword v20, v[8:9] nt
	v_or_b32_e32 v8, 10, v15
	v_mad_i64_i32 v[8:9], s[18:19], v8, s67, v[6:7]
	flat_load_dword v21, v[8:9] nt
	v_or_b32_e32 v8, 12, v15
	v_mad_i64_i32 v[8:9], s[18:19], v8, s67, v[6:7]
	flat_load_dword v22, v[8:9] nt
	v_or_b32_e32 v8, 14, v15
	v_mad_i64_i32 v[8:9], s[18:19], v8, s67, v[6:7]
	flat_load_dword v23, v[8:9] nt
	v_or_b32_e32 v8, 16, v15
	v_mad_i64_i32 v[8:9], s[18:19], v8, s67, v[6:7]
	flat_load_dword v24, v[8:9] nt
	v_or_b32_e32 v8, 18, v15
	v_mad_i64_i32 v[8:9], s[18:19], v8, s67, v[6:7]
	flat_load_dword v25, v[8:9] nt
	v_or_b32_e32 v8, 20, v15
	v_mad_i64_i32 v[8:9], s[18:19], v8, s67, v[6:7]
	flat_load_dword v26, v[8:9] nt
	v_or_b32_e32 v8, 22, v15
	v_mad_i64_i32 v[8:9], s[18:19], v8, s67, v[6:7]
	flat_load_dword v27, v[8:9] nt
	v_or_b32_e32 v8, 24, v15
	v_mad_i64_i32 v[8:9], s[18:19], v8, s67, v[6:7]
	flat_load_dword v28, v[8:9] nt
	v_or_b32_e32 v8, 26, v15
	v_mad_i64_i32 v[8:9], s[18:19], v8, s67, v[6:7]
	flat_load_dword v29, v[8:9] nt
	v_or_b32_e32 v8, 28, v15
	v_mad_i64_i32 v[8:9], s[18:19], v8, s67, v[6:7]
	flat_load_dword v30, v[8:9] nt
	v_or_b32_e32 v8, 30, v15
	v_mad_i64_i32 v[8:9], s[18:19], v8, s67, v[6:7]
	flat_load_dword v31, v[8:9] nt
	v_or_b32_e32 v8, 32, v15
	v_mad_i64_i32 v[8:9], s[18:19], v8, s67, v[6:7]
	flat_load_dword v32, v[8:9] nt
	v_or_b32_e32 v8, 34, v15
	v_mad_i64_i32 v[8:9], s[18:19], v8, s67, v[6:7]
	flat_load_dword v33, v[8:9] nt
	v_or_b32_e32 v8, 36, v15
	v_mad_i64_i32 v[8:9], s[18:19], v8, s67, v[6:7]
	flat_load_dword v34, v[8:9] nt
	v_or_b32_e32 v8, 38, v15
	v_mad_i64_i32 v[8:9], s[18:19], v8, s67, v[6:7]
	flat_load_dword v35, v[8:9] nt
	v_or_b32_e32 v8, 40, v15
	v_mad_i64_i32 v[8:9], s[18:19], v8, s67, v[6:7]
	flat_load_dword v36, v[8:9] nt
	v_or_b32_e32 v8, 42, v15
	v_mad_i64_i32 v[8:9], s[18:19], v8, s67, v[6:7]
	flat_load_dword v37, v[8:9] nt
	v_or_b32_e32 v8, 44, v15
	v_mad_i64_i32 v[8:9], s[18:19], v8, s67, v[6:7]
	flat_load_dword v38, v[8:9] nt
	v_or_b32_e32 v8, 46, v15
	v_mad_i64_i32 v[8:9], s[18:19], v8, s67, v[6:7]
	flat_load_dword v39, v[8:9] nt
	v_or_b32_e32 v8, 48, v15
	v_mad_i64_i32 v[8:9], s[18:19], v8, s67, v[6:7]
	flat_load_dword v40, v[8:9] nt
	v_or_b32_e32 v8, 50, v15
	v_mad_i64_i32 v[8:9], s[18:19], v8, s67, v[6:7]
	flat_load_dword v41, v[8:9] nt
	v_or_b32_e32 v8, 52, v15
	v_mad_i64_i32 v[8:9], s[18:19], v8, s67, v[6:7]
	flat_load_dword v42, v[8:9] nt
	v_or_b32_e32 v8, 54, v15
	v_mad_i64_i32 v[8:9], s[18:19], v8, s67, v[6:7]
	flat_load_dword v43, v[8:9] nt
	v_or_b32_e32 v8, 56, v15
	v_mad_i64_i32 v[8:9], s[18:19], v8, s67, v[6:7]
	flat_load_dword v44, v[8:9] nt
	v_or_b32_e32 v8, 58, v15
	v_mad_i64_i32 v[8:9], s[18:19], v8, s67, v[6:7]
	flat_load_dword v45, v[8:9] nt
	v_or_b32_e32 v8, 60, v15
	v_mad_i64_i32 v[8:9], s[18:19], v8, s67, v[6:7]
	flat_load_dword v8, v[8:9] nt
	v_or_b32_e32 v9, 62, v15
	v_mad_i64_i32 v[6:7], s[18:19], v9, s67, v[6:7]
	flat_load_dword v6, v[6:7] nt
	v_add_u32_e32 v7, 0x400, v5
	s_waitcnt vmcnt(0) lgkmcnt(0)
	ds_write2_b32 v5, v16, v17 offset1:66
	ds_write2_b32 v5, v18, v19 offset0:132 offset1:198
	ds_write2_b32 v7, v20, v21 offset0:8 offset1:74
	ds_write2_b32 v7, v22, v23 offset0:140 offset1:206
	v_add_u32_e32 v7, 0x800, v5
	ds_write2_b32 v7, v24, v25 offset0:16 offset1:82
	ds_write2_b32 v7, v26, v27 offset0:148 offset1:214
	v_add_u32_e32 v7, 0xc00, v5
	ds_write2_b32 v7, v28, v29 offset0:24 offset1:90
	ds_write2_b32 v7, v30, v31 offset0:156 offset1:222
	v_add_u32_e32 v7, 0x1000, v5
	ds_write2_b32 v7, v32, v33 offset0:32 offset1:98
	ds_write2_b32 v7, v34, v35 offset0:164 offset1:230
	v_add_u32_e32 v7, 0x1400, v5
	ds_write2_b32 v7, v36, v37 offset0:40 offset1:106
	ds_write2_b32 v7, v38, v39 offset0:172 offset1:238
	v_add_u32_e32 v7, 0x1800, v5
	ds_write2_b32 v7, v40, v41 offset0:48 offset1:114
	ds_write2_b32 v7, v42, v43 offset0:180 offset1:246
	v_add_u32_e32 v7, 0x1c00, v5
	ds_write2_b32 v7, v44, v45 offset0:56 offset1:122
	ds_write2_b32 v7, v8, v6 offset0:188 offset1:254
	s_waitcnt lgkmcnt(0)
	ds_read2_b32 v[96:97], v11 offset1:33
	ds_read2_b32 v[98:99], v11 offset0:66 offset1:99
	ds_read2_b32 v[100:101], v11 offset0:132 offset1:165
	ds_read2_b32 v[102:103], v11 offset0:198 offset1:231
	ds_read2_b32 v[104:105], v11 offset0:8 offset1:41
	ds_read2_b32 v[106:107], v11 offset0:74 offset1:107
	ds_read2_b32 v[108:109], v11 offset0:140 offset1:173
	ds_read2_b32 v[110:111], v11 offset0:206 offset1:239
	ds_read2_b32 v[112:113], v11 offset0:16 offset1:49
	ds_read2_b32 v[114:115], v11 offset0:82 offset1:115
	ds_read2_b32 v[116:117], v11 offset0:148 offset1:181
	ds_read2_b32 v[118:119], v11 offset0:214 offset1:247
	ds_read2_b32 v[120:121], v11 offset0:24 offset1:57
	ds_read2_b32 v[122:123], v11 offset0:90 offset1:123
	ds_read2_b32 v[124:125], v11 offset0:156 offset1:189
	s_waitcnt lgkmcnt(7)
	ds_read2_b32 v[126:127], v11 offset0:222 offset1:255
	v_cvt_pk_bf16_f32 v16, v96, v97
	s_ashr_i32 s3, s2, 31
	v_cvt_pk_bf16_f32 v17, v98, v99
	s_lshl_b64 s[2:3], s[2:3], 1
	v_cvt_pk_bf16_f32 v18, v100, v101
	s_add_u32 s2, s15, s2
	v_cvt_pk_bf16_f32 v19, v102, v103
	v_or_b32_e32 v8, s0, v10
	s_addc_u32 s3, s16, s3
	v_lshlrev_b32_e32 v6, 1, v4
	v_mov_b32_e32 v7, v2
	v_ashrrev_i32_e32 v9, 31, v8
	v_lshl_add_u64 v[6:7], s[2:3], 0, v[6:7]
	v_lshlrev_b64 v[8:9], 11, v[8:9]
	v_lshl_add_u64 v[8:9], v[6:7], 0, v[8:9]
	global_store_dwordx4 v[8:9], v[16:19], off
	s_nop 1
	s_mov_b32 s19, s69
	v_cvt_pk_bf16_f32 v16, v104, v105
	v_cvt_pk_bf16_f32 v17, v106, v107
	v_cvt_pk_bf16_f32 v18, v108, v109
	v_cvt_pk_bf16_f32 v19, v110, v111
	v_or_b32_e32 v8, s0, v12
	v_ashrrev_i32_e32 v9, 31, v8
	v_lshlrev_b64 v[8:9], 11, v[8:9]
	v_lshl_add_u64 v[8:9], v[6:7], 0, v[8:9]
	global_store_dwordx4 v[8:9], v[16:19], off
	s_nop 1
	s_waitcnt lgkmcnt(0)
	v_cvt_pk_bf16_f32 v16, v112, v113
	v_cvt_pk_bf16_f32 v17, v114, v115
	v_cvt_pk_bf16_f32 v18, v116, v117
	v_cvt_pk_bf16_f32 v19, v118, v119
	v_or_b32_e32 v8, s0, v13
	v_ashrrev_i32_e32 v9, 31, v8
	v_lshlrev_b64 v[8:9], 11, v[8:9]
	v_lshl_add_u64 v[8:9], v[6:7], 0, v[8:9]
	global_store_dwordx4 v[8:9], v[16:19], off
	s_nop 1
	v_cvt_pk_bf16_f32 v16, v120, v121
	v_cvt_pk_bf16_f32 v17, v122, v123
	v_cvt_pk_bf16_f32 v18, v124, v125
	v_cvt_pk_bf16_f32 v19, v126, v127
	v_or_b32_e32 v8, s0, v14
	v_ashrrev_i32_e32 v9, 31, v8
	v_lshlrev_b64 v[8:9], 11, v[8:9]
	v_lshl_add_u64 v[6:7], v[6:7], 0, v[8:9]
	global_store_dwordx4 v[6:7], v[16:19], off
	s_waitcnt lgkmcnt(0)
	s_branch .LBB0_797

.LBB0_836:
	s_mul_hi_i32 s0, s4, 0x2aaaaaab
	s_lshr_b32 s1, s0, 31
	s_ashr_i32 s0, s0, 9
	s_add_i32 s0, s0, s1
	v_mov_b32_e32 v7, s33
	s_mul_i32 s1, s0, 0xfffff400
	ds_read_b64 v[14:15], v7
	s_add_i32 s1, s4, s1
	s_mul_hi_i32 s5, s1, 0x2aaaaaab
	s_lshr_b32 s7, s5, 31
	s_ashr_i32 s5, s5, 5
	s_add_i32 s7, s5, s7
	s_mul_i32 s5, s7, 0xc0
	s_mul_i32 s3, s0, 0x1800000
	s_waitcnt lgkmcnt(0)
	v_readfirstlane_b32 s8, v14
	s_sub_i32 s1, s1, s5
	s_mul_hi_i32 s2, s0, 0x1800000
	v_readfirstlane_b32 s9, v15
	s_add_u32 s3, s8, s3
	s_mul_hi_i32 s6, s0, 0xc00000
	s_mul_i32 s0, s0, 0xc00000
	s_addc_u32 s10, s9, s2
	s_add_u32 s5, s62, s0
	s_addc_u32 s6, s63, s6
	s_lshl_b32 s0, s1, 5
	s_ashr_i32 s1, s0, 31
	s_lshl_b32 s2, s7, 6
	s_lshl_b64 s[8:9], s[0:1], 2
	s_add_u32 s8, s3, s8
	v_mov_b32_e32 v5, v2
	v_or_b32_e32 v7, s2, v1
	s_addc_u32 s9, s10, s9
	v_or_b32_e32 v26, 10, v7
	v_or_b32_e32 v28, 12, v7
	v_or_b32_e32 v30, 14, v7
	v_or_b32_e32 v32, 16, v7
	v_or_b32_e32 v34, 18, v7
	v_or_b32_e32 v36, 20, v7
	v_or_b32_e32 v38, 22, v7
	v_or_b32_e32 v40, 24, v7
	v_or_b32_e32 v42, 26, v7
	v_or_b32_e32 v44, 28, v7
	v_or_b32_e32 v46, 30, v7
	v_or_b32_e32 v48, 32, v7
	v_or_b32_e32 v50, 34, v7
	v_or_b32_e32 v52, 36, v7
	v_lshl_add_u64 v[14:15], s[8:9], 0, v[4:5]
	v_or_b32_e32 v13, 2, v7
	v_or_b32_e32 v20, 4, v7
	v_or_b32_e32 v22, 6, v7
	v_or_b32_e32 v24, 8, v7
	v_or_b32_e32 v54, 38, v7
	v_or_b32_e32 v56, 40, v7
	v_or_b32_e32 v58, 42, v7
	v_or_b32_e32 v60, 44, v7
	v_or_b32_e32 v62, 46, v7
	v_or_b32_e32 v64, 48, v7
	v_or_b32_e32 v66, 50, v7
	v_or_b32_e32 v68, 52, v7
	v_or_b32_e32 v70, 54, v7
	v_or_b32_e32 v72, 56, v7
	v_or_b32_e32 v74, 58, v7
	v_or_b32_e32 v76, 60, v7
	v_or_b32_e32 v78, 62, v7
	v_mad_i64_i32 v[16:17], s[8:9], v7, s67, v[14:15]
	v_mad_i64_i32 v[26:27], s[8:9], v26, s67, v[14:15]
	v_mad_i64_i32 v[28:29], s[8:9], v28, s67, v[14:15]
	v_mad_i64_i32 v[30:31], s[8:9], v30, s67, v[14:15]
	v_mad_i64_i32 v[32:33], s[8:9], v32, s67, v[14:15]
	v_mad_i64_i32 v[34:35], s[8:9], v34, s67, v[14:15]
	v_mad_i64_i32 v[36:37], s[8:9], v36, s67, v[14:15]
	v_mad_i64_i32 v[38:39], s[8:9], v38, s67, v[14:15]
	v_mad_i64_i32 v[40:41], s[8:9], v40, s67, v[14:15]
	v_mad_i64_i32 v[42:43], s[8:9], v42, s67, v[14:15]
	v_mad_i64_i32 v[44:45], s[8:9], v44, s67, v[14:15]
	v_mad_i64_i32 v[46:47], s[8:9], v46, s67, v[14:15]
	v_mad_i64_i32 v[48:49], s[8:9], v48, s67, v[14:15]
	v_mad_i64_i32 v[50:51], s[8:9], v50, s67, v[14:15]
	v_mad_i64_i32 v[52:53], s[8:9], v52, s67, v[14:15]
	v_mad_i64_i32 v[18:19], s[8:9], v13, s67, v[14:15]
	v_mad_i64_i32 v[20:21], s[8:9], v20, s67, v[14:15]
	v_mad_i64_i32 v[22:23], s[8:9], v22, s67, v[14:15]
	v_mad_i64_i32 v[24:25], s[8:9], v24, s67, v[14:15]
	v_mad_i64_i32 v[54:55], s[8:9], v54, s67, v[14:15]
	v_mad_i64_i32 v[56:57], s[8:9], v56, s67, v[14:15]
	v_mad_i64_i32 v[58:59], s[8:9], v58, s67, v[14:15]
	v_mad_i64_i32 v[60:61], s[8:9], v60, s67, v[14:15]
	v_mad_i64_i32 v[62:63], s[8:9], v62, s67, v[14:15]
	v_mad_i64_i32 v[64:65], s[8:9], v64, s67, v[14:15]
	v_mad_i64_i32 v[66:67], s[8:9], v66, s67, v[14:15]
	v_mad_i64_i32 v[68:69], s[8:9], v68, s67, v[14:15]
	v_mad_i64_i32 v[70:71], s[8:9], v70, s67, v[14:15]
	v_mad_i64_i32 v[72:73], s[8:9], v72, s67, v[14:15]
	v_mad_i64_i32 v[74:75], s[8:9], v74, s67, v[14:15]
	v_mad_i64_i32 v[76:77], s[8:9], v76, s67, v[14:15]
	v_mad_i64_i32 v[14:15], s[8:9], v78, s67, v[14:15]
	flat_load_dword v5, v[16:17] nt
	flat_load_dword v13, v[18:19] nt
	flat_load_dword v78, v[20:21] nt
	flat_load_dword v79, v[22:23] nt
	flat_load_dword v80, v[24:25] nt
	s_nop 0
	flat_load_dword v26, v[26:27] nt
	s_nop 0
	flat_load_dword v27, v[28:29] nt
	s_nop 0
	flat_load_dword v28, v[30:31] nt
	flat_load_dword v29, v[32:33] nt
	s_nop 0
	flat_load_dword v30, v[34:35] nt
	flat_load_dword v31, v[36:37] nt
	flat_load_dword v32, v[38:39] nt
	flat_load_dword v33, v[40:41] nt
	s_nop 0
	flat_load_dword v34, v[42:43] nt
	flat_load_dword v35, v[44:45] nt
	flat_load_dword v36, v[46:47] nt
	flat_load_dword v37, v[48:49] nt
	flat_load_dword v38, v[50:51] nt
	flat_load_dword v39, v[52:53] nt
	flat_load_dword v40, v[54:55] nt
	flat_load_dword v41, v[56:57] nt
	flat_load_dword v42, v[58:59] nt
	flat_load_dword v43, v[60:61] nt
	flat_load_dword v44, v[62:63] nt
	flat_load_dword v45, v[64:65] nt
	flat_load_dword v46, v[66:67] nt
	flat_load_dword v47, v[68:69] nt
	flat_load_dword v48, v[70:71] nt
	flat_load_dword v49, v[72:73] nt
	flat_load_dword v50, v[74:75] nt
	flat_load_dword v51, v[76:77] nt
	flat_load_dword v52, v[14:15] nt
	s_ashr_i32 s3, s2, 31
	s_lshl_b64 s[2:3], s[2:3], 1
	v_or_b32_e32 v14, s0, v3
	s_add_u32 s2, s5, s2
	v_add_u32_e32 v53, 0x400, v12
	v_add_u32_e32 v54, 0x800, v12
	v_add_u32_e32 v55, 0xc00, v12
	v_add_u32_e32 v56, 0x1000, v12
	v_add_u32_e32 v57, 0x1400, v12
	v_add_u32_e32 v58, 0x1800, v12
	v_add_u32_e32 v59, 0x1c00, v12
	v_mov_b32_e32 v7, v2
	v_or_b32_e32 v16, s0, v9
	v_ashrrev_i32_e32 v15, 31, v14
	s_addc_u32 s3, s6, s3
	s_waitcnt vmcnt(0) lgkmcnt(0)
	ds_write2_b32 v12, v5, v13 offset1:66
	ds_write2_b32 v12, v78, v79 offset0:132 offset1:198
	ds_write2_b32 v53, v80, v26 offset0:8 offset1:74
	ds_write2_b32 v53, v27, v28 offset0:140 offset1:206
	ds_write2_b32 v54, v29, v30 offset0:16 offset1:82
	ds_write2_b32 v54, v31, v32 offset0:148 offset1:214
	ds_write2_b32 v55, v33, v34 offset0:24 offset1:90
	ds_write2_b32 v55, v35, v36 offset0:156 offset1:222
	ds_write2_b32 v56, v37, v38 offset0:32 offset1:98
	ds_write2_b32 v56, v39, v40 offset0:164 offset1:230
	ds_write2_b32 v57, v41, v42 offset0:40 offset1:106
	ds_write2_b32 v57, v43, v44 offset0:172 offset1:238
	ds_write2_b32 v58, v45, v46 offset0:48 offset1:114
	ds_write2_b32 v58, v47, v48 offset0:180 offset1:246
	ds_write2_b32 v59, v49, v50 offset0:56 offset1:122
	ds_write2_b32 v59, v51, v52 offset0:188 offset1:254
	v_ashrrev_i32_e32 v17, 31, v16
	v_lshlrev_b64 v[14:15], 11, v[14:15]
	v_lshl_add_u64 v[20:21], s[2:3], 0, v[6:7]
	s_waitcnt lgkmcnt(0)
	v_lshlrev_b64 v[16:17], 11, v[16:17]
	v_lshl_add_u64 v[22:23], v[20:21], 0, v[14:15]
	ds_read2_b32 v[96:97], v8 offset1:33
	ds_read2_b32 v[98:99], v8 offset0:66 offset1:99
	ds_read2_b32 v[100:101], v8 offset0:132 offset1:165
	ds_read2_b32 v[102:103], v8 offset0:198 offset1:231
	ds_read2_b32 v[104:105], v8 offset0:8 offset1:41
	ds_read2_b32 v[106:107], v8 offset0:74 offset1:107
	ds_read2_b32 v[108:109], v8 offset0:140 offset1:173
	ds_read2_b32 v[110:111], v8 offset0:206 offset1:239
	ds_read2_b32 v[112:113], v8 offset0:16 offset1:49
	ds_read2_b32 v[114:115], v8 offset0:82 offset1:115
	ds_read2_b32 v[116:117], v8 offset0:148 offset1:181
	ds_read2_b32 v[118:119], v8 offset0:214 offset1:247
	ds_read2_b32 v[120:121], v8 offset0:24 offset1:57
	ds_read2_b32 v[122:123], v8 offset0:90 offset1:123
	ds_read2_b32 v[124:125], v8 offset0:156 offset1:189
	s_waitcnt lgkmcnt(7)
	ds_read2_b32 v[126:127], v8 offset0:222 offset1:255
	v_lshl_add_u64 v[24:25], v[20:21], 0, v[16:17]
	v_cvt_pk_bf16_f32 v14, v96, v97
	v_cvt_pk_bf16_f32 v15, v98, v99
	v_cvt_pk_bf16_f32 v16, v100, v101
	v_cvt_pk_bf16_f32 v17, v102, v103
	global_store_dwordx4 v[22:23], v[14:17], off
	s_nop 1
	v_or_b32_e32 v18, s0, v10
	v_ashrrev_i32_e32 v19, 31, v18
	v_cvt_pk_bf16_f32 v14, v104, v105
	v_cvt_pk_bf16_f32 v15, v106, v107
	v_cvt_pk_bf16_f32 v16, v108, v109
	v_cvt_pk_bf16_f32 v17, v110, v111
	global_store_dwordx4 v[24:25], v[14:17], off
	s_nop 1
	s_waitcnt lgkmcnt(0)
	v_lshlrev_b64 v[18:19], 11, v[18:19]
	v_lshl_add_u64 v[18:19], v[20:21], 0, v[18:19]
	v_cvt_pk_bf16_f32 v14, v112, v113
	v_cvt_pk_bf16_f32 v15, v114, v115
	v_cvt_pk_bf16_f32 v16, v116, v117
	v_cvt_pk_bf16_f32 v17, v118, v119
	global_store_dwordx4 v[18:19], v[14:17], off
	s_nop 1
	s_add_i32 s4, s4, s68
	s_cmpk_lt_i32 s4, 0x3000
	v_cvt_pk_bf16_f32 v14, v120, v121
	v_or_b32_e32 v22, s0, v11
	v_ashrrev_i32_e32 v23, 31, v22
	v_lshlrev_b64 v[22:23], 11, v[22:23]
	v_cvt_pk_bf16_f32 v15, v122, v123
	v_lshl_add_u64 v[20:21], v[20:21], 0, v[22:23]
	v_cvt_pk_bf16_f32 v16, v124, v125
	v_cvt_pk_bf16_f32 v17, v126, v127
	global_store_dwordx4 v[20:21], v[14:17], off
	s_waitcnt lgkmcnt(0)
	s_cbranch_scc1 .LBB0_836
